# hand-written CONV epilogue (weights loaded once up front, packed FMA conv in place, 16-byte ACT/HALO stores) + wave_sum tails via row_bcast
# speedup vs baseline: 1.0207x; 1.0171x over previous
.LBB0_134:
	s_lshl_b32 s94, s69, 8
	s_add_i32 s94, s94, s10
	v_or_b32_e32 v180, s94, v1
	s_cmp_lt_i32 s81, 2
	s_mov_b64 s[38:39], -1
	s_cbranch_scc1 .LBB0_178
	s_mov_b64 s[56:57], -1
	s_mov_b64 s[44:45], 0
	s_cmp_lt_i32 s81, 4
	s_mov_b64 s[38:39], 0
	s_cbranch_scc1 .LBB0_173
	s_cmp_eq_u32 s81, 4
	s_mov_b64 s[38:39], -1
	s_cbranch_scc0 .LBB0_170
	s_mov_b32 s74, 0xbfb8aa3b
	s_mov_b32 s88, 1.0
	s_mov_b64 s[44:45], 0x1600
	s_lshl_b32 s38, s54, 9
	v_lshl_add_u32 v228, v172, 2, s38
	v_mov_b32_e32 v229, 0
	v_lshl_add_u64 v[212:213], s[48:49], 0, v[228:229]
	v_lshl_add_u64 v[214:215], s[34:35], 0, v[228:229]
	v_lshl_add_u64 v[216:217], s[36:37], 0, v[228:229]
	v_lshl_add_u64 v[218:219], s[50:51], 0, v[228:229]
	s_add_u32 s56, s48, 0x2c00
	s_addc_u32 s57, s49, 0
	v_lshl_add_u64 v[220:221], s[56:57], 0, v[228:229]
	s_add_u32 s56, s34, 0x2c00
	s_addc_u32 s57, s35, 0
	v_lshl_add_u64 v[222:223], s[56:57], 0, v[228:229]
	s_add_u32 s56, s36, 0x2c00
	s_addc_u32 s57, s37, 0
	v_lshl_add_u64 v[224:225], s[56:57], 0, v[228:229]
	s_add_u32 s56, s50, 0x2c00
	s_addc_u32 s57, s51, 0
	v_lshl_add_u64 v[226:227], s[56:57], 0, v[228:229]
	global_load_dwordx4 v[130:133], v[212:213], off
	global_load_dwordx4 v[146:149], v[212:213], off offset:16
	global_load_dwordx4 v[134:137], v[214:215], off
	global_load_dwordx4 v[150:153], v[214:215], off offset:16
	global_load_dwordx4 v[138:141], v[216:217], off
	global_load_dwordx4 v[154:157], v[216:217], off offset:16
	global_load_dwordx4 v[142:145], v[218:219], off
	global_load_dwordx4 v[158:161], v[218:219], off offset:16
	global_load_dwordx4 v[180:183], v[220:221], off
	global_load_dwordx4 v[196:199], v[220:221], off offset:16
	global_load_dwordx4 v[184:187], v[222:223], off
	global_load_dwordx4 v[200:203], v[222:223], off offset:16
	global_load_dwordx4 v[188:191], v[224:225], off
	global_load_dwordx4 v[204:207], v[224:225], off offset:16
	global_load_dwordx4 v[192:195], v[226:227], off
	global_load_dwordx4 v[208:211], v[226:227], off offset:16
	s_lshl_b32 s38, s69, 4
	s_lshl_b32 s39, s76, 2
	s_add_i32 s38, s38, s39
	s_mul_i32 s38, s38, 0x2c00
	s_lshl_b32 s39, s54, 9
	s_add_i32 s38, s38, s39
	s_add_u32 s56, s22, s38
	s_addc_u32 s57, s23, 0
	v_mov_b32_e32 v252, 0x5800
	v_cndmask_b32_e64 v252, v252, 0, s[40:41]
	v_lshl_add_u32 v252, v172, 1, v252
	v_mov_b32_e32 v253, 0
	v_lshl_add_u64 v[244:245], s[56:57], 0, v[252:253]
	s_add_u32 s56, s56, 0x2c00
	s_addc_u32 s57, s57, 0
	v_lshl_add_u64 v[246:247], s[56:57], 0, v[252:253]
	s_add_u32 s56, s56, 0x13400
	s_addc_u32 s57, s57, 0
	v_lshl_add_u64 v[248:249], s[56:57], 0, v[252:253]
	s_add_u32 s56, s56, 0x2c00
	s_addc_u32 s57, s57, 0
	v_lshl_add_u64 v[250:251], s[56:57], 0, v[252:253]
	v_cmp_eq_u32_e32 vcc, 15, v1
	s_mov_b64 exec, s[40:41]
	v_cvt_pk_bf16_f32 v216, v126, v127
	v_cvt_pk_bf16_f32 v217, v128, v129
	v_cvt_pk_bf16_f32 v218, v122, v123
	v_cvt_pk_bf16_f32 v219, v124, v125
	global_store_dwordx4 v[244:245], v[216:219], off
	v_cvt_pk_bf16_f32 v220, v110, v111
	v_cvt_pk_bf16_f32 v221, v112, v113
	v_cvt_pk_bf16_f32 v222, v106, v107
	v_cvt_pk_bf16_f32 v223, v108, v109
	global_store_dwordx4 v[246:247], v[220:223], off
	v_cvt_pk_bf16_f32 v224, v118, v119
	v_cvt_pk_bf16_f32 v225, v120, v121
	v_cvt_pk_bf16_f32 v226, v114, v115
	v_cvt_pk_bf16_f32 v227, v116, v117
	global_store_dwordx4 v[244:245], v[224:227], off offset:256
	v_cvt_pk_bf16_f32 v216, v102, v103
	v_cvt_pk_bf16_f32 v217, v104, v105
	v_cvt_pk_bf16_f32 v218, v98, v99
	v_cvt_pk_bf16_f32 v219, v100, v101
	global_store_dwordx4 v[246:247], v[216:219], off offset:256
	v_cvt_pk_bf16_f32 v220, v62, v63
	v_cvt_pk_bf16_f32 v221, v64, v65
	v_cvt_pk_bf16_f32 v222, v58, v59
	v_cvt_pk_bf16_f32 v223, v60, v61
	global_store_dwordx4 v[248:249], v[220:223], off
	v_cvt_pk_bf16_f32 v224, v46, v47
	v_cvt_pk_bf16_f32 v225, v48, v49
	v_cvt_pk_bf16_f32 v226, v42, v43
	v_cvt_pk_bf16_f32 v227, v44, v45
	global_store_dwordx4 v[250:251], v[224:227], off
	v_cvt_pk_bf16_f32 v216, v54, v55
	v_cvt_pk_bf16_f32 v217, v56, v57
	v_cvt_pk_bf16_f32 v218, v50, v51
	v_cvt_pk_bf16_f32 v219, v52, v53
	global_store_dwordx4 v[248:249], v[216:219], off offset:256
	v_cvt_pk_bf16_f32 v220, v38, v39
	v_cvt_pk_bf16_f32 v221, v40, v41
	v_cvt_pk_bf16_f32 v222, v34, v35
	v_cvt_pk_bf16_f32 v223, v36, v37
	global_store_dwordx4 v[250:251], v[220:223], off offset:256
	s_mov_b64 exec, vcc
	v_cvt_pk_bf16_f32 v224, v94, v95
	v_cvt_pk_bf16_f32 v225, v96, v97
	v_cvt_pk_bf16_f32 v226, v90, v91
	v_cvt_pk_bf16_f32 v227, v92, v93
	global_store_dwordx4 v[244:245], v[224:227], off
	v_cvt_pk_bf16_f32 v216, v78, v79
	v_cvt_pk_bf16_f32 v217, v80, v81
	v_cvt_pk_bf16_f32 v218, v74, v75
	v_cvt_pk_bf16_f32 v219, v76, v77
	global_store_dwordx4 v[246:247], v[216:219], off
	v_cvt_pk_bf16_f32 v220, v86, v87
	v_cvt_pk_bf16_f32 v221, v88, v89
	v_cvt_pk_bf16_f32 v222, v82, v83
	v_cvt_pk_bf16_f32 v223, v84, v85
	global_store_dwordx4 v[244:245], v[220:223], off offset:256
	v_cvt_pk_bf16_f32 v224, v70, v71
	v_cvt_pk_bf16_f32 v225, v72, v73
	v_cvt_pk_bf16_f32 v226, v66, v67
	v_cvt_pk_bf16_f32 v227, v68, v69
	global_store_dwordx4 v[246:247], v[224:227], off offset:256
	v_cvt_pk_bf16_f32 v216, v30, v31
	v_cvt_pk_bf16_f32 v217, v32, v33
	v_cvt_pk_bf16_f32 v218, v26, v27
	v_cvt_pk_bf16_f32 v219, v28, v29
	global_store_dwordx4 v[248:249], v[216:219], off
	v_cvt_pk_bf16_f32 v220, v14, v15
	v_cvt_pk_bf16_f32 v221, v16, v17
	v_cvt_pk_bf16_f32 v222, v10, v11
	v_cvt_pk_bf16_f32 v223, v12, v13
	global_store_dwordx4 v[250:251], v[220:223], off
	v_cvt_pk_bf16_f32 v224, v22, v23
	v_cvt_pk_bf16_f32 v225, v24, v25
	v_cvt_pk_bf16_f32 v226, v18, v19
	v_cvt_pk_bf16_f32 v227, v20, v21
	global_store_dwordx4 v[248:249], v[224:227], off offset:256
	v_cvt_pk_bf16_f32 v216, v6, v7
	v_cvt_pk_bf16_f32 v217, v8, v9
	v_cvt_pk_bf16_f32 v218, v2, v3
	v_cvt_pk_bf16_f32 v219, v4, v5
	global_store_dwordx4 v[250:251], v[216:219], off offset:256
	s_mov_b64 exec, -1
	v_mul_u32_u24_e32 v230, 0x5800, v1
	v_lshl_add_u32 v230, v172, 1, v230
	v_mov_b32_e32 v231, 0
	v_mov_b32_dpp v212, v78 row_shr:1 row_mask:0xf bank_mask:0xf bound_ctrl:1
	v_mov_b32_dpp v213, v79 row_shr:1 row_mask:0xf bank_mask:0xf bound_ctrl:1
	v_mov_b32_dpp v214, v80 row_shr:1 row_mask:0xf bank_mask:0xf bound_ctrl:1
	v_mov_b32_dpp v215, v81 row_shr:1 row_mask:0xf bank_mask:0xf bound_ctrl:1
	v_mov_b32_dpp v216, v74 row_shr:1 row_mask:0xf bank_mask:0xf bound_ctrl:1
	v_mov_b32_dpp v217, v75 row_shr:1 row_mask:0xf bank_mask:0xf bound_ctrl:1
	v_mov_b32_dpp v218, v76 row_shr:1 row_mask:0xf bank_mask:0xf bound_ctrl:1
	v_mov_b32_dpp v219, v77 row_shr:1 row_mask:0xf bank_mask:0xf bound_ctrl:1
	v_mov_b32_dpp v220, v94 row_shr:1 row_mask:0xf bank_mask:0xf bound_ctrl:1
	v_mov_b32_dpp v221, v95 row_shr:1 row_mask:0xf bank_mask:0xf bound_ctrl:1
	v_mov_b32_dpp v222, v96 row_shr:1 row_mask:0xf bank_mask:0xf bound_ctrl:1
	v_mov_b32_dpp v223, v97 row_shr:1 row_mask:0xf bank_mask:0xf bound_ctrl:1
	v_mov_b32_dpp v224, v90 row_shr:1 row_mask:0xf bank_mask:0xf bound_ctrl:1
	v_mov_b32_dpp v225, v91 row_shr:1 row_mask:0xf bank_mask:0xf bound_ctrl:1
	v_mov_b32_dpp v226, v92 row_shr:1 row_mask:0xf bank_mask:0xf bound_ctrl:1
	v_mov_b32_dpp v227, v93 row_shr:1 row_mask:0xf bank_mask:0xf bound_ctrl:1
	s_waitcnt vmcnt(16)
	v_pk_fma_f32 v[78:79], v[138:139], v[78:79], v[142:143]
	v_pk_fma_f32 v[80:81], v[140:141], v[80:81], v[144:145]
	v_pk_fma_f32 v[74:75], v[154:155], v[74:75], v[158:159]
	v_pk_fma_f32 v[76:77], v[156:157], v[76:77], v[160:161]
	v_pk_fma_f32 v[78:79], v[134:135], v[94:95], v[78:79]
	v_pk_fma_f32 v[80:81], v[136:137], v[96:97], v[80:81]
	v_pk_fma_f32 v[74:75], v[150:151], v[90:91], v[74:75]
	v_pk_fma_f32 v[76:77], v[152:153], v[92:93], v[76:77]
	v_pk_fma_f32 v[78:79], v[130:131], v[110:111], v[78:79]
	v_pk_fma_f32 v[80:81], v[132:133], v[112:113], v[80:81]
	v_pk_fma_f32 v[74:75], v[146:147], v[106:107], v[74:75]
	v_pk_fma_f32 v[76:77], v[148:149], v[108:109], v[76:77]
	v_pk_fma_f32 v[94:95], v[138:139], v[94:95], v[142:143]
	v_pk_fma_f32 v[96:97], v[140:141], v[96:97], v[144:145]
	v_pk_fma_f32 v[90:91], v[154:155], v[90:91], v[158:159]
	v_pk_fma_f32 v[92:93], v[156:157], v[92:93], v[160:161]
	v_pk_fma_f32 v[94:95], v[134:135], v[110:111], v[94:95]
	v_pk_fma_f32 v[96:97], v[136:137], v[112:113], v[96:97]
	v_pk_fma_f32 v[90:91], v[150:151], v[106:107], v[90:91]
	v_pk_fma_f32 v[92:93], v[152:153], v[108:109], v[92:93]
	v_pk_fma_f32 v[94:95], v[130:131], v[126:127], v[94:95]
	v_pk_fma_f32 v[96:97], v[132:133], v[128:129], v[96:97]
	v_pk_fma_f32 v[90:91], v[146:147], v[122:123], v[90:91]
	v_pk_fma_f32 v[92:93], v[148:149], v[124:125], v[92:93]
	v_pk_fma_f32 v[110:111], v[138:139], v[110:111], v[142:143]
	v_pk_fma_f32 v[112:113], v[140:141], v[112:113], v[144:145]
	v_pk_fma_f32 v[106:107], v[154:155], v[106:107], v[158:159]
	v_pk_fma_f32 v[108:109], v[156:157], v[108:109], v[160:161]
	v_pk_fma_f32 v[110:111], v[134:135], v[126:127], v[110:111]
	v_pk_fma_f32 v[112:113], v[136:137], v[128:129], v[112:113]
	v_pk_fma_f32 v[106:107], v[150:151], v[122:123], v[106:107]
	v_pk_fma_f32 v[108:109], v[152:153], v[124:125], v[108:109]
	v_pk_fma_f32 v[110:111], v[130:131], v[212:213], v[110:111]
	v_pk_fma_f32 v[112:113], v[132:133], v[214:215], v[112:113]
	v_pk_fma_f32 v[106:107], v[146:147], v[216:217], v[106:107]
	v_pk_fma_f32 v[108:109], v[148:149], v[218:219], v[108:109]
	v_pk_fma_f32 v[126:127], v[138:139], v[126:127], v[142:143]
	v_pk_fma_f32 v[128:129], v[140:141], v[128:129], v[144:145]
	v_pk_fma_f32 v[122:123], v[154:155], v[122:123], v[158:159]
	v_pk_fma_f32 v[124:125], v[156:157], v[124:125], v[160:161]
	v_pk_fma_f32 v[126:127], v[134:135], v[212:213], v[126:127]
	v_pk_fma_f32 v[128:129], v[136:137], v[214:215], v[128:129]
	v_pk_fma_f32 v[122:123], v[150:151], v[216:217], v[122:123]
	v_pk_fma_f32 v[124:125], v[152:153], v[218:219], v[124:125]
	v_pk_fma_f32 v[126:127], v[130:131], v[220:221], v[126:127]
	v_pk_fma_f32 v[128:129], v[132:133], v[222:223], v[128:129]
	v_pk_fma_f32 v[122:123], v[146:147], v[224:225], v[122:123]
	v_pk_fma_f32 v[124:125], v[148:149], v[226:227], v[124:125]
	v_mov_b32_dpp v212, v70 row_shr:1 row_mask:0xf bank_mask:0xf bound_ctrl:1
	v_mov_b32_dpp v213, v71 row_shr:1 row_mask:0xf bank_mask:0xf bound_ctrl:1
	v_mov_b32_dpp v214, v72 row_shr:1 row_mask:0xf bank_mask:0xf bound_ctrl:1
	v_mov_b32_dpp v215, v73 row_shr:1 row_mask:0xf bank_mask:0xf bound_ctrl:1
	v_mov_b32_dpp v216, v66 row_shr:1 row_mask:0xf bank_mask:0xf bound_ctrl:1
	v_mov_b32_dpp v217, v67 row_shr:1 row_mask:0xf bank_mask:0xf bound_ctrl:1
	v_mov_b32_dpp v218, v68 row_shr:1 row_mask:0xf bank_mask:0xf bound_ctrl:1
	v_mov_b32_dpp v219, v69 row_shr:1 row_mask:0xf bank_mask:0xf bound_ctrl:1
	v_mov_b32_dpp v220, v86 row_shr:1 row_mask:0xf bank_mask:0xf bound_ctrl:1
	v_mov_b32_dpp v221, v87 row_shr:1 row_mask:0xf bank_mask:0xf bound_ctrl:1
	v_mov_b32_dpp v222, v88 row_shr:1 row_mask:0xf bank_mask:0xf bound_ctrl:1
	v_mov_b32_dpp v223, v89 row_shr:1 row_mask:0xf bank_mask:0xf bound_ctrl:1
	v_mov_b32_dpp v224, v82 row_shr:1 row_mask:0xf bank_mask:0xf bound_ctrl:1
	v_mov_b32_dpp v225, v83 row_shr:1 row_mask:0xf bank_mask:0xf bound_ctrl:1
	v_mov_b32_dpp v226, v84 row_shr:1 row_mask:0xf bank_mask:0xf bound_ctrl:1
	v_mov_b32_dpp v227, v85 row_shr:1 row_mask:0xf bank_mask:0xf bound_ctrl:1
	v_pk_fma_f32 v[70:71], v[188:189], v[70:71], v[192:193]
	v_pk_fma_f32 v[72:73], v[190:191], v[72:73], v[194:195]
	v_pk_fma_f32 v[66:67], v[204:205], v[66:67], v[208:209]
	v_pk_fma_f32 v[68:69], v[206:207], v[68:69], v[210:211]
	v_pk_fma_f32 v[70:71], v[184:185], v[86:87], v[70:71]
	v_pk_fma_f32 v[72:73], v[186:187], v[88:89], v[72:73]
	v_pk_fma_f32 v[66:67], v[200:201], v[82:83], v[66:67]
	v_pk_fma_f32 v[68:69], v[202:203], v[84:85], v[68:69]
	v_pk_fma_f32 v[70:71], v[180:181], v[102:103], v[70:71]
	v_pk_fma_f32 v[72:73], v[182:183], v[104:105], v[72:73]
	v_pk_fma_f32 v[66:67], v[196:197], v[98:99], v[66:67]
	v_pk_fma_f32 v[68:69], v[198:199], v[100:101], v[68:69]
	v_pk_fma_f32 v[86:87], v[188:189], v[86:87], v[192:193]
	v_pk_fma_f32 v[88:89], v[190:191], v[88:89], v[194:195]
	v_pk_fma_f32 v[82:83], v[204:205], v[82:83], v[208:209]
	v_pk_fma_f32 v[84:85], v[206:207], v[84:85], v[210:211]
	v_pk_fma_f32 v[86:87], v[184:185], v[102:103], v[86:87]
	v_pk_fma_f32 v[88:89], v[186:187], v[104:105], v[88:89]
	v_pk_fma_f32 v[82:83], v[200:201], v[98:99], v[82:83]
	v_pk_fma_f32 v[84:85], v[202:203], v[100:101], v[84:85]
	v_pk_fma_f32 v[86:87], v[180:181], v[118:119], v[86:87]
	v_pk_fma_f32 v[88:89], v[182:183], v[120:121], v[88:89]
	v_pk_fma_f32 v[82:83], v[196:197], v[114:115], v[82:83]
	v_pk_fma_f32 v[84:85], v[198:199], v[116:117], v[84:85]
	v_pk_fma_f32 v[102:103], v[188:189], v[102:103], v[192:193]
	v_pk_fma_f32 v[104:105], v[190:191], v[104:105], v[194:195]
	v_pk_fma_f32 v[98:99], v[204:205], v[98:99], v[208:209]
	v_pk_fma_f32 v[100:101], v[206:207], v[100:101], v[210:211]
	v_pk_fma_f32 v[102:103], v[184:185], v[118:119], v[102:103]
	v_pk_fma_f32 v[104:105], v[186:187], v[120:121], v[104:105]
	v_pk_fma_f32 v[98:99], v[200:201], v[114:115], v[98:99]
	v_pk_fma_f32 v[100:101], v[202:203], v[116:117], v[100:101]
	v_pk_fma_f32 v[102:103], v[180:181], v[212:213], v[102:103]
	v_pk_fma_f32 v[104:105], v[182:183], v[214:215], v[104:105]
	v_pk_fma_f32 v[98:99], v[196:197], v[216:217], v[98:99]
	v_pk_fma_f32 v[100:101], v[198:199], v[218:219], v[100:101]
	v_pk_fma_f32 v[118:119], v[188:189], v[118:119], v[192:193]
	v_pk_fma_f32 v[120:121], v[190:191], v[120:121], v[194:195]
	v_pk_fma_f32 v[114:115], v[204:205], v[114:115], v[208:209]
	v_pk_fma_f32 v[116:117], v[206:207], v[116:117], v[210:211]
	v_pk_fma_f32 v[118:119], v[184:185], v[212:213], v[118:119]
	v_pk_fma_f32 v[120:121], v[186:187], v[214:215], v[120:121]
	v_pk_fma_f32 v[114:115], v[200:201], v[216:217], v[114:115]
	v_pk_fma_f32 v[116:117], v[202:203], v[218:219], v[116:117]
	v_pk_fma_f32 v[118:119], v[180:181], v[220:221], v[118:119]
	v_pk_fma_f32 v[120:121], v[182:183], v[222:223], v[120:121]
	v_pk_fma_f32 v[114:115], v[196:197], v[224:225], v[114:115]
	v_pk_fma_f32 v[116:117], v[198:199], v[226:227], v[116:117]
	v_pk_mul_f32 v[212:213], v[126:127], s[74:75] op_sel_hi:[1,0]
	v_pk_mul_f32 v[214:215], v[128:129], s[74:75] op_sel_hi:[1,0]
	v_pk_mul_f32 v[216:217], v[122:123], s[74:75] op_sel_hi:[1,0]
	v_pk_mul_f32 v[218:219], v[124:125], s[74:75] op_sel_hi:[1,0]
	v_pk_mul_f32 v[220:221], v[110:111], s[74:75] op_sel_hi:[1,0]
	v_pk_mul_f32 v[222:223], v[112:113], s[74:75] op_sel_hi:[1,0]
	v_pk_mul_f32 v[224:225], v[106:107], s[74:75] op_sel_hi:[1,0]
	v_pk_mul_f32 v[226:227], v[108:109], s[74:75] op_sel_hi:[1,0]
	v_exp_f32_e32 v212, v212
	v_exp_f32_e32 v213, v213
	v_exp_f32_e32 v214, v214
	v_exp_f32_e32 v215, v215
	v_exp_f32_e32 v216, v216
	v_exp_f32_e32 v217, v217
	v_exp_f32_e32 v218, v218
	v_exp_f32_e32 v219, v219
	v_exp_f32_e32 v220, v220
	v_exp_f32_e32 v221, v221
	v_exp_f32_e32 v222, v222
	v_exp_f32_e32 v223, v223
	v_exp_f32_e32 v224, v224
	v_exp_f32_e32 v225, v225
	v_exp_f32_e32 v226, v226
	v_exp_f32_e32 v227, v227
	v_pk_add_f32 v[212:213], v[212:213], s[88:89] op_sel_hi:[1,0]
	v_pk_add_f32 v[214:215], v[214:215], s[88:89] op_sel_hi:[1,0]
	v_pk_add_f32 v[216:217], v[216:217], s[88:89] op_sel_hi:[1,0]
	v_pk_add_f32 v[218:219], v[218:219], s[88:89] op_sel_hi:[1,0]
	v_pk_add_f32 v[220:221], v[220:221], s[88:89] op_sel_hi:[1,0]
	v_pk_add_f32 v[222:223], v[222:223], s[88:89] op_sel_hi:[1,0]
	v_pk_add_f32 v[224:225], v[224:225], s[88:89] op_sel_hi:[1,0]
	v_pk_add_f32 v[226:227], v[226:227], s[88:89] op_sel_hi:[1,0]
	v_rcp_f32_e32 v212, v212
	v_rcp_f32_e32 v213, v213
	v_rcp_f32_e32 v214, v214
	v_rcp_f32_e32 v215, v215
	v_rcp_f32_e32 v216, v216
	v_rcp_f32_e32 v217, v217
	v_rcp_f32_e32 v218, v218
	v_rcp_f32_e32 v219, v219
	v_rcp_f32_e32 v220, v220
	v_rcp_f32_e32 v221, v221
	v_rcp_f32_e32 v222, v222
	v_rcp_f32_e32 v223, v223
	v_rcp_f32_e32 v224, v224
	v_rcp_f32_e32 v225, v225
	v_rcp_f32_e32 v226, v226
	v_rcp_f32_e32 v227, v227
	v_pk_mul_f32 v[126:127], v[126:127], v[212:213]
	v_pk_mul_f32 v[128:129], v[128:129], v[214:215]
	v_pk_mul_f32 v[122:123], v[122:123], v[216:217]
	v_pk_mul_f32 v[124:125], v[124:125], v[218:219]
	v_pk_mul_f32 v[110:111], v[110:111], v[220:221]
	v_pk_mul_f32 v[112:113], v[112:113], v[222:223]
	v_pk_mul_f32 v[106:107], v[106:107], v[224:225]
	v_pk_mul_f32 v[108:109], v[108:109], v[226:227]
	v_pk_mul_f32 v[118:119], v[118:119], v[126:127]
	v_pk_mul_f32 v[120:121], v[120:121], v[128:129]
	v_pk_mul_f32 v[114:115], v[114:115], v[122:123]
	v_pk_mul_f32 v[116:117], v[116:117], v[124:125]
	v_pk_mul_f32 v[102:103], v[102:103], v[110:111]
	v_pk_mul_f32 v[104:105], v[104:105], v[112:113]
	v_pk_mul_f32 v[98:99], v[98:99], v[106:107]
	v_pk_mul_f32 v[100:101], v[100:101], v[108:109]
	v_pk_mul_f32 v[212:213], v[94:95], s[74:75] op_sel_hi:[1,0]
	v_pk_mul_f32 v[214:215], v[96:97], s[74:75] op_sel_hi:[1,0]
	v_pk_mul_f32 v[216:217], v[90:91], s[74:75] op_sel_hi:[1,0]
	v_pk_mul_f32 v[218:219], v[92:93], s[74:75] op_sel_hi:[1,0]
	v_pk_mul_f32 v[220:221], v[78:79], s[74:75] op_sel_hi:[1,0]
	v_pk_mul_f32 v[222:223], v[80:81], s[74:75] op_sel_hi:[1,0]
	v_pk_mul_f32 v[224:225], v[74:75], s[74:75] op_sel_hi:[1,0]
	v_pk_mul_f32 v[226:227], v[76:77], s[74:75] op_sel_hi:[1,0]
	v_exp_f32_e32 v212, v212
	v_exp_f32_e32 v213, v213
	v_exp_f32_e32 v214, v214
	v_exp_f32_e32 v215, v215
	v_exp_f32_e32 v216, v216
	v_exp_f32_e32 v217, v217
	v_exp_f32_e32 v218, v218
	v_exp_f32_e32 v219, v219
	v_exp_f32_e32 v220, v220
	v_exp_f32_e32 v221, v221
	v_exp_f32_e32 v222, v222
	v_exp_f32_e32 v223, v223
	v_exp_f32_e32 v224, v224
	v_exp_f32_e32 v225, v225
	v_exp_f32_e32 v226, v226
	v_exp_f32_e32 v227, v227
	v_pk_add_f32 v[212:213], v[212:213], s[88:89] op_sel_hi:[1,0]
	v_pk_add_f32 v[214:215], v[214:215], s[88:89] op_sel_hi:[1,0]
	v_pk_add_f32 v[216:217], v[216:217], s[88:89] op_sel_hi:[1,0]
	v_pk_add_f32 v[218:219], v[218:219], s[88:89] op_sel_hi:[1,0]
	v_pk_add_f32 v[220:221], v[220:221], s[88:89] op_sel_hi:[1,0]
	v_pk_add_f32 v[222:223], v[222:223], s[88:89] op_sel_hi:[1,0]
	v_pk_add_f32 v[224:225], v[224:225], s[88:89] op_sel_hi:[1,0]
	v_pk_add_f32 v[226:227], v[226:227], s[88:89] op_sel_hi:[1,0]
	v_rcp_f32_e32 v212, v212
	v_rcp_f32_e32 v213, v213
	v_rcp_f32_e32 v214, v214
	v_rcp_f32_e32 v215, v215
	v_rcp_f32_e32 v216, v216
	v_rcp_f32_e32 v217, v217
	v_rcp_f32_e32 v218, v218
	v_rcp_f32_e32 v219, v219
	v_rcp_f32_e32 v220, v220
	v_rcp_f32_e32 v221, v221
	v_rcp_f32_e32 v222, v222
	v_rcp_f32_e32 v223, v223
	v_rcp_f32_e32 v224, v224
	v_rcp_f32_e32 v225, v225
	v_rcp_f32_e32 v226, v226
	v_rcp_f32_e32 v227, v227
	v_pk_mul_f32 v[94:95], v[94:95], v[212:213]
	v_pk_mul_f32 v[96:97], v[96:97], v[214:215]
	v_pk_mul_f32 v[90:91], v[90:91], v[216:217]
	v_pk_mul_f32 v[92:93], v[92:93], v[218:219]
	v_pk_mul_f32 v[78:79], v[78:79], v[220:221]
	v_pk_mul_f32 v[80:81], v[80:81], v[222:223]
	v_pk_mul_f32 v[74:75], v[74:75], v[224:225]
	v_pk_mul_f32 v[76:77], v[76:77], v[226:227]
	v_pk_mul_f32 v[86:87], v[86:87], v[94:95]
	v_pk_mul_f32 v[88:89], v[88:89], v[96:97]
	v_pk_mul_f32 v[82:83], v[82:83], v[90:91]
	v_pk_mul_f32 v[84:85], v[84:85], v[92:93]
	v_pk_mul_f32 v[70:71], v[70:71], v[78:79]
	v_pk_mul_f32 v[72:73], v[72:73], v[80:81]
	v_pk_mul_f32 v[66:67], v[66:67], v[74:75]
	v_pk_mul_f32 v[68:69], v[68:69], v[76:77]
	s_lshl_b32 s38, s69, 8
	s_lshl_b32 s39, s76, 6
	s_add_i32 s38, s38, s39
	s_mul_i32 s38, s38, 0x1600
	s_lshl_b32 s39, s54, 8
	s_add_u32 s56, s18, s38
	s_addc_u32 s57, s19, 0
	s_add_u32 s56, s56, s39
	s_addc_u32 s57, s57, 0
	v_lshl_add_u64 v[228:229], s[56:57], 0, v[230:231]
	v_cvt_pk_bf16_f32 v212, v118, v119
	v_cvt_pk_bf16_f32 v213, v120, v121
	v_cvt_pk_bf16_f32 v214, v114, v115
	v_cvt_pk_bf16_f32 v215, v116, v117
	global_store_dwordx4 v[228:229], v[212:215], off
	v_lshl_add_u64 v[228:229], v[228:229], 0, s[44:45]
	v_cvt_pk_bf16_f32 v216, v102, v103
	v_cvt_pk_bf16_f32 v217, v104, v105
	v_cvt_pk_bf16_f32 v218, v98, v99
	v_cvt_pk_bf16_f32 v219, v100, v101
	global_store_dwordx4 v[228:229], v[216:219], off
	v_lshl_add_u64 v[228:229], v[228:229], 0, s[44:45]
	v_cvt_pk_bf16_f32 v220, v86, v87
	v_cvt_pk_bf16_f32 v221, v88, v89
	v_cvt_pk_bf16_f32 v222, v82, v83
	v_cvt_pk_bf16_f32 v223, v84, v85
	global_store_dwordx4 v[228:229], v[220:223], off
	v_lshl_add_u64 v[228:229], v[228:229], 0, s[44:45]
	v_cvt_pk_bf16_f32 v212, v70, v71
	v_cvt_pk_bf16_f32 v213, v72, v73
	v_cvt_pk_bf16_f32 v214, v66, v67
	v_cvt_pk_bf16_f32 v215, v68, v69
	global_store_dwordx4 v[228:229], v[212:215], off
	s_nop 1
	v_mov_b32_dpp v212, v14 row_shr:1 row_mask:0xf bank_mask:0xf bound_ctrl:1
	v_mov_b32_dpp v213, v15 row_shr:1 row_mask:0xf bank_mask:0xf bound_ctrl:1
	v_mov_b32_dpp v214, v16 row_shr:1 row_mask:0xf bank_mask:0xf bound_ctrl:1
	v_mov_b32_dpp v215, v17 row_shr:1 row_mask:0xf bank_mask:0xf bound_ctrl:1
	v_mov_b32_dpp v216, v10 row_shr:1 row_mask:0xf bank_mask:0xf bound_ctrl:1
	v_mov_b32_dpp v217, v11 row_shr:1 row_mask:0xf bank_mask:0xf bound_ctrl:1
	v_mov_b32_dpp v218, v12 row_shr:1 row_mask:0xf bank_mask:0xf bound_ctrl:1
	v_mov_b32_dpp v219, v13 row_shr:1 row_mask:0xf bank_mask:0xf bound_ctrl:1
	v_mov_b32_dpp v220, v30 row_shr:1 row_mask:0xf bank_mask:0xf bound_ctrl:1
	v_mov_b32_dpp v221, v31 row_shr:1 row_mask:0xf bank_mask:0xf bound_ctrl:1
	v_mov_b32_dpp v222, v32 row_shr:1 row_mask:0xf bank_mask:0xf bound_ctrl:1
	v_mov_b32_dpp v223, v33 row_shr:1 row_mask:0xf bank_mask:0xf bound_ctrl:1
	v_mov_b32_dpp v224, v26 row_shr:1 row_mask:0xf bank_mask:0xf bound_ctrl:1
	v_mov_b32_dpp v225, v27 row_shr:1 row_mask:0xf bank_mask:0xf bound_ctrl:1
	v_mov_b32_dpp v226, v28 row_shr:1 row_mask:0xf bank_mask:0xf bound_ctrl:1
	v_mov_b32_dpp v227, v29 row_shr:1 row_mask:0xf bank_mask:0xf bound_ctrl:1
	v_pk_fma_f32 v[14:15], v[138:139], v[14:15], v[142:143]
	v_pk_fma_f32 v[16:17], v[140:141], v[16:17], v[144:145]
	v_pk_fma_f32 v[10:11], v[154:155], v[10:11], v[158:159]
	v_pk_fma_f32 v[12:13], v[156:157], v[12:13], v[160:161]
	v_pk_fma_f32 v[14:15], v[134:135], v[30:31], v[14:15]
	v_pk_fma_f32 v[16:17], v[136:137], v[32:33], v[16:17]
	v_pk_fma_f32 v[10:11], v[150:151], v[26:27], v[10:11]
	v_pk_fma_f32 v[12:13], v[152:153], v[28:29], v[12:13]
	v_pk_fma_f32 v[14:15], v[130:131], v[46:47], v[14:15]
	v_pk_fma_f32 v[16:17], v[132:133], v[48:49], v[16:17]
	v_pk_fma_f32 v[10:11], v[146:147], v[42:43], v[10:11]
	v_pk_fma_f32 v[12:13], v[148:149], v[44:45], v[12:13]
	v_pk_fma_f32 v[30:31], v[138:139], v[30:31], v[142:143]
	v_pk_fma_f32 v[32:33], v[140:141], v[32:33], v[144:145]
	v_pk_fma_f32 v[26:27], v[154:155], v[26:27], v[158:159]
	v_pk_fma_f32 v[28:29], v[156:157], v[28:29], v[160:161]
	v_pk_fma_f32 v[30:31], v[134:135], v[46:47], v[30:31]
	v_pk_fma_f32 v[32:33], v[136:137], v[48:49], v[32:33]
	v_pk_fma_f32 v[26:27], v[150:151], v[42:43], v[26:27]
	v_pk_fma_f32 v[28:29], v[152:153], v[44:45], v[28:29]
	v_pk_fma_f32 v[30:31], v[130:131], v[62:63], v[30:31]
	v_pk_fma_f32 v[32:33], v[132:133], v[64:65], v[32:33]
	v_pk_fma_f32 v[26:27], v[146:147], v[58:59], v[26:27]
	v_pk_fma_f32 v[28:29], v[148:149], v[60:61], v[28:29]
	v_pk_fma_f32 v[46:47], v[138:139], v[46:47], v[142:143]
	v_pk_fma_f32 v[48:49], v[140:141], v[48:49], v[144:145]
	v_pk_fma_f32 v[42:43], v[154:155], v[42:43], v[158:159]
	v_pk_fma_f32 v[44:45], v[156:157], v[44:45], v[160:161]
	v_pk_fma_f32 v[46:47], v[134:135], v[62:63], v[46:47]
	v_pk_fma_f32 v[48:49], v[136:137], v[64:65], v[48:49]
	v_pk_fma_f32 v[42:43], v[150:151], v[58:59], v[42:43]
	v_pk_fma_f32 v[44:45], v[152:153], v[60:61], v[44:45]
	v_pk_fma_f32 v[46:47], v[130:131], v[212:213], v[46:47]
	v_pk_fma_f32 v[48:49], v[132:133], v[214:215], v[48:49]
	v_pk_fma_f32 v[42:43], v[146:147], v[216:217], v[42:43]
	v_pk_fma_f32 v[44:45], v[148:149], v[218:219], v[44:45]
	v_pk_fma_f32 v[62:63], v[138:139], v[62:63], v[142:143]
	v_pk_fma_f32 v[64:65], v[140:141], v[64:65], v[144:145]
	v_pk_fma_f32 v[58:59], v[154:155], v[58:59], v[158:159]
	v_pk_fma_f32 v[60:61], v[156:157], v[60:61], v[160:161]
	v_pk_fma_f32 v[62:63], v[134:135], v[212:213], v[62:63]
	v_pk_fma_f32 v[64:65], v[136:137], v[214:215], v[64:65]
	v_pk_fma_f32 v[58:59], v[150:151], v[216:217], v[58:59]
	v_pk_fma_f32 v[60:61], v[152:153], v[218:219], v[60:61]
	v_pk_fma_f32 v[62:63], v[130:131], v[220:221], v[62:63]
	v_pk_fma_f32 v[64:65], v[132:133], v[222:223], v[64:65]
	v_pk_fma_f32 v[58:59], v[146:147], v[224:225], v[58:59]
	v_pk_fma_f32 v[60:61], v[148:149], v[226:227], v[60:61]
	v_mov_b32_dpp v212, v6 row_shr:1 row_mask:0xf bank_mask:0xf bound_ctrl:1
	v_mov_b32_dpp v213, v7 row_shr:1 row_mask:0xf bank_mask:0xf bound_ctrl:1
	v_mov_b32_dpp v214, v8 row_shr:1 row_mask:0xf bank_mask:0xf bound_ctrl:1
	v_mov_b32_dpp v215, v9 row_shr:1 row_mask:0xf bank_mask:0xf bound_ctrl:1
	v_mov_b32_dpp v216, v2 row_shr:1 row_mask:0xf bank_mask:0xf bound_ctrl:1
	v_mov_b32_dpp v217, v3 row_shr:1 row_mask:0xf bank_mask:0xf bound_ctrl:1
	v_mov_b32_dpp v218, v4 row_shr:1 row_mask:0xf bank_mask:0xf bound_ctrl:1
	v_mov_b32_dpp v219, v5 row_shr:1 row_mask:0xf bank_mask:0xf bound_ctrl:1
	v_mov_b32_dpp v220, v22 row_shr:1 row_mask:0xf bank_mask:0xf bound_ctrl:1
	v_mov_b32_dpp v221, v23 row_shr:1 row_mask:0xf bank_mask:0xf bound_ctrl:1
	v_mov_b32_dpp v222, v24 row_shr:1 row_mask:0xf bank_mask:0xf bound_ctrl:1
	v_mov_b32_dpp v223, v25 row_shr:1 row_mask:0xf bank_mask:0xf bound_ctrl:1
	v_mov_b32_dpp v224, v18 row_shr:1 row_mask:0xf bank_mask:0xf bound_ctrl:1
	v_mov_b32_dpp v225, v19 row_shr:1 row_mask:0xf bank_mask:0xf bound_ctrl:1
	v_mov_b32_dpp v226, v20 row_shr:1 row_mask:0xf bank_mask:0xf bound_ctrl:1
	v_mov_b32_dpp v227, v21 row_shr:1 row_mask:0xf bank_mask:0xf bound_ctrl:1
	v_pk_fma_f32 v[6:7], v[188:189], v[6:7], v[192:193]
	v_pk_fma_f32 v[8:9], v[190:191], v[8:9], v[194:195]
	v_pk_fma_f32 v[2:3], v[204:205], v[2:3], v[208:209]
	v_pk_fma_f32 v[4:5], v[206:207], v[4:5], v[210:211]
	v_pk_fma_f32 v[6:7], v[184:185], v[22:23], v[6:7]
	v_pk_fma_f32 v[8:9], v[186:187], v[24:25], v[8:9]
	v_pk_fma_f32 v[2:3], v[200:201], v[18:19], v[2:3]
	v_pk_fma_f32 v[4:5], v[202:203], v[20:21], v[4:5]
	v_pk_fma_f32 v[6:7], v[180:181], v[38:39], v[6:7]
	v_pk_fma_f32 v[8:9], v[182:183], v[40:41], v[8:9]
	v_pk_fma_f32 v[2:3], v[196:197], v[34:35], v[2:3]
	v_pk_fma_f32 v[4:5], v[198:199], v[36:37], v[4:5]
	v_pk_fma_f32 v[22:23], v[188:189], v[22:23], v[192:193]
	v_pk_fma_f32 v[24:25], v[190:191], v[24:25], v[194:195]
	v_pk_fma_f32 v[18:19], v[204:205], v[18:19], v[208:209]
	v_pk_fma_f32 v[20:21], v[206:207], v[20:21], v[210:211]
	v_pk_fma_f32 v[22:23], v[184:185], v[38:39], v[22:23]
	v_pk_fma_f32 v[24:25], v[186:187], v[40:41], v[24:25]
	v_pk_fma_f32 v[18:19], v[200:201], v[34:35], v[18:19]
	v_pk_fma_f32 v[20:21], v[202:203], v[36:37], v[20:21]
	v_pk_fma_f32 v[22:23], v[180:181], v[54:55], v[22:23]
	v_pk_fma_f32 v[24:25], v[182:183], v[56:57], v[24:25]
	v_pk_fma_f32 v[18:19], v[196:197], v[50:51], v[18:19]
	v_pk_fma_f32 v[20:21], v[198:199], v[52:53], v[20:21]
	v_pk_fma_f32 v[38:39], v[188:189], v[38:39], v[192:193]
	v_pk_fma_f32 v[40:41], v[190:191], v[40:41], v[194:195]
	v_pk_fma_f32 v[34:35], v[204:205], v[34:35], v[208:209]
	v_pk_fma_f32 v[36:37], v[206:207], v[36:37], v[210:211]
	v_pk_fma_f32 v[38:39], v[184:185], v[54:55], v[38:39]
	v_pk_fma_f32 v[40:41], v[186:187], v[56:57], v[40:41]
	v_pk_fma_f32 v[34:35], v[200:201], v[50:51], v[34:35]
	v_pk_fma_f32 v[36:37], v[202:203], v[52:53], v[36:37]
	v_pk_fma_f32 v[38:39], v[180:181], v[212:213], v[38:39]
	v_pk_fma_f32 v[40:41], v[182:183], v[214:215], v[40:41]
	v_pk_fma_f32 v[34:35], v[196:197], v[216:217], v[34:35]
	v_pk_fma_f32 v[36:37], v[198:199], v[218:219], v[36:37]
	v_pk_fma_f32 v[54:55], v[188:189], v[54:55], v[192:193]
	v_pk_fma_f32 v[56:57], v[190:191], v[56:57], v[194:195]
	v_pk_fma_f32 v[50:51], v[204:205], v[50:51], v[208:209]
	v_pk_fma_f32 v[52:53], v[206:207], v[52:53], v[210:211]
	v_pk_fma_f32 v[54:55], v[184:185], v[212:213], v[54:55]
	v_pk_fma_f32 v[56:57], v[186:187], v[214:215], v[56:57]
	v_pk_fma_f32 v[50:51], v[200:201], v[216:217], v[50:51]
	v_pk_fma_f32 v[52:53], v[202:203], v[218:219], v[52:53]
	v_pk_fma_f32 v[54:55], v[180:181], v[220:221], v[54:55]
	v_pk_fma_f32 v[56:57], v[182:183], v[222:223], v[56:57]
	v_pk_fma_f32 v[50:51], v[196:197], v[224:225], v[50:51]
	v_pk_fma_f32 v[52:53], v[198:199], v[226:227], v[52:53]
	v_pk_mul_f32 v[212:213], v[62:63], s[74:75] op_sel_hi:[1,0]
	v_pk_mul_f32 v[214:215], v[64:65], s[74:75] op_sel_hi:[1,0]
	v_pk_mul_f32 v[216:217], v[58:59], s[74:75] op_sel_hi:[1,0]
	v_pk_mul_f32 v[218:219], v[60:61], s[74:75] op_sel_hi:[1,0]
	v_pk_mul_f32 v[220:221], v[46:47], s[74:75] op_sel_hi:[1,0]
	v_pk_mul_f32 v[222:223], v[48:49], s[74:75] op_sel_hi:[1,0]
	v_pk_mul_f32 v[224:225], v[42:43], s[74:75] op_sel_hi:[1,0]
	v_pk_mul_f32 v[226:227], v[44:45], s[74:75] op_sel_hi:[1,0]
	v_exp_f32_e32 v212, v212
	v_exp_f32_e32 v213, v213
	v_exp_f32_e32 v214, v214
	v_exp_f32_e32 v215, v215
	v_exp_f32_e32 v216, v216
	v_exp_f32_e32 v217, v217
	v_exp_f32_e32 v218, v218
	v_exp_f32_e32 v219, v219
	v_exp_f32_e32 v220, v220
	v_exp_f32_e32 v221, v221
	v_exp_f32_e32 v222, v222
	v_exp_f32_e32 v223, v223
	v_exp_f32_e32 v224, v224
	v_exp_f32_e32 v225, v225
	v_exp_f32_e32 v226, v226
	v_exp_f32_e32 v227, v227
	v_pk_add_f32 v[212:213], v[212:213], s[88:89] op_sel_hi:[1,0]
	v_pk_add_f32 v[214:215], v[214:215], s[88:89] op_sel_hi:[1,0]
	v_pk_add_f32 v[216:217], v[216:217], s[88:89] op_sel_hi:[1,0]
	v_pk_add_f32 v[218:219], v[218:219], s[88:89] op_sel_hi:[1,0]
	v_pk_add_f32 v[220:221], v[220:221], s[88:89] op_sel_hi:[1,0]
	v_pk_add_f32 v[222:223], v[222:223], s[88:89] op_sel_hi:[1,0]
	v_pk_add_f32 v[224:225], v[224:225], s[88:89] op_sel_hi:[1,0]
	v_pk_add_f32 v[226:227], v[226:227], s[88:89] op_sel_hi:[1,0]
	v_rcp_f32_e32 v212, v212
	v_rcp_f32_e32 v213, v213
	v_rcp_f32_e32 v214, v214
	v_rcp_f32_e32 v215, v215
	v_rcp_f32_e32 v216, v216
	v_rcp_f32_e32 v217, v217
	v_rcp_f32_e32 v218, v218
	v_rcp_f32_e32 v219, v219
	v_rcp_f32_e32 v220, v220
	v_rcp_f32_e32 v221, v221
	v_rcp_f32_e32 v222, v222
	v_rcp_f32_e32 v223, v223
	v_rcp_f32_e32 v224, v224
	v_rcp_f32_e32 v225, v225
	v_rcp_f32_e32 v226, v226
	v_rcp_f32_e32 v227, v227
	v_pk_mul_f32 v[62:63], v[62:63], v[212:213]
	v_pk_mul_f32 v[64:65], v[64:65], v[214:215]
	v_pk_mul_f32 v[58:59], v[58:59], v[216:217]
	v_pk_mul_f32 v[60:61], v[60:61], v[218:219]
	v_pk_mul_f32 v[46:47], v[46:47], v[220:221]
	v_pk_mul_f32 v[48:49], v[48:49], v[222:223]
	v_pk_mul_f32 v[42:43], v[42:43], v[224:225]
	v_pk_mul_f32 v[44:45], v[44:45], v[226:227]
	v_pk_mul_f32 v[54:55], v[54:55], v[62:63]
	v_pk_mul_f32 v[56:57], v[56:57], v[64:65]
	v_pk_mul_f32 v[50:51], v[50:51], v[58:59]
	v_pk_mul_f32 v[52:53], v[52:53], v[60:61]
	v_pk_mul_f32 v[38:39], v[38:39], v[46:47]
	v_pk_mul_f32 v[40:41], v[40:41], v[48:49]
	v_pk_mul_f32 v[34:35], v[34:35], v[42:43]
	v_pk_mul_f32 v[36:37], v[36:37], v[44:45]
	v_pk_mul_f32 v[212:213], v[30:31], s[74:75] op_sel_hi:[1,0]
	v_pk_mul_f32 v[214:215], v[32:33], s[74:75] op_sel_hi:[1,0]
	v_pk_mul_f32 v[216:217], v[26:27], s[74:75] op_sel_hi:[1,0]
	v_pk_mul_f32 v[218:219], v[28:29], s[74:75] op_sel_hi:[1,0]
	v_pk_mul_f32 v[220:221], v[14:15], s[74:75] op_sel_hi:[1,0]
	v_pk_mul_f32 v[222:223], v[16:17], s[74:75] op_sel_hi:[1,0]
	v_pk_mul_f32 v[224:225], v[10:11], s[74:75] op_sel_hi:[1,0]
	v_pk_mul_f32 v[226:227], v[12:13], s[74:75] op_sel_hi:[1,0]
	v_exp_f32_e32 v212, v212
	v_exp_f32_e32 v213, v213
	v_exp_f32_e32 v214, v214
	v_exp_f32_e32 v215, v215
	v_exp_f32_e32 v216, v216
	v_exp_f32_e32 v217, v217
	v_exp_f32_e32 v218, v218
	v_exp_f32_e32 v219, v219
	v_exp_f32_e32 v220, v220
	v_exp_f32_e32 v221, v221
	v_exp_f32_e32 v222, v222
	v_exp_f32_e32 v223, v223
	v_exp_f32_e32 v224, v224
	v_exp_f32_e32 v225, v225
	v_exp_f32_e32 v226, v226
	v_exp_f32_e32 v227, v227
	v_pk_add_f32 v[212:213], v[212:213], s[88:89] op_sel_hi:[1,0]
	v_pk_add_f32 v[214:215], v[214:215], s[88:89] op_sel_hi:[1,0]
	v_pk_add_f32 v[216:217], v[216:217], s[88:89] op_sel_hi:[1,0]
	v_pk_add_f32 v[218:219], v[218:219], s[88:89] op_sel_hi:[1,0]
	v_pk_add_f32 v[220:221], v[220:221], s[88:89] op_sel_hi:[1,0]
	v_pk_add_f32 v[222:223], v[222:223], s[88:89] op_sel_hi:[1,0]
	v_pk_add_f32 v[224:225], v[224:225], s[88:89] op_sel_hi:[1,0]
	v_pk_add_f32 v[226:227], v[226:227], s[88:89] op_sel_hi:[1,0]
	v_rcp_f32_e32 v212, v212
	v_rcp_f32_e32 v213, v213
	v_rcp_f32_e32 v214, v214
	v_rcp_f32_e32 v215, v215
	v_rcp_f32_e32 v216, v216
	v_rcp_f32_e32 v217, v217
	v_rcp_f32_e32 v218, v218
	v_rcp_f32_e32 v219, v219
	v_rcp_f32_e32 v220, v220
	v_rcp_f32_e32 v221, v221
	v_rcp_f32_e32 v222, v222
	v_rcp_f32_e32 v223, v223
	v_rcp_f32_e32 v224, v224
	v_rcp_f32_e32 v225, v225
	v_rcp_f32_e32 v226, v226
	v_rcp_f32_e32 v227, v227
	v_pk_mul_f32 v[30:31], v[30:31], v[212:213]
	v_pk_mul_f32 v[32:33], v[32:33], v[214:215]
	v_pk_mul_f32 v[26:27], v[26:27], v[216:217]
	v_pk_mul_f32 v[28:29], v[28:29], v[218:219]
	v_pk_mul_f32 v[14:15], v[14:15], v[220:221]
	v_pk_mul_f32 v[16:17], v[16:17], v[222:223]
	v_pk_mul_f32 v[10:11], v[10:11], v[224:225]
	v_pk_mul_f32 v[12:13], v[12:13], v[226:227]
	v_pk_mul_f32 v[22:23], v[22:23], v[30:31]
	v_pk_mul_f32 v[24:25], v[24:25], v[32:33]
	v_pk_mul_f32 v[18:19], v[18:19], v[26:27]
	v_pk_mul_f32 v[20:21], v[20:21], v[28:29]
	v_pk_mul_f32 v[6:7], v[6:7], v[14:15]
	v_pk_mul_f32 v[8:9], v[8:9], v[16:17]
	v_pk_mul_f32 v[2:3], v[2:3], v[10:11]
	v_pk_mul_f32 v[4:5], v[4:5], v[12:13]
	s_lshl_b32 s38, s69, 8
	s_lshl_b32 s39, s76, 6
	s_add_i32 s38, s38, s39
	s_addk_i32 s38, 0x80
	s_mul_i32 s38, s38, 0x1600
	s_lshl_b32 s39, s54, 8
	s_add_u32 s56, s18, s38
	s_addc_u32 s57, s19, 0
	s_add_u32 s56, s56, s39
	s_addc_u32 s57, s57, 0
	v_lshl_add_u64 v[228:229], s[56:57], 0, v[230:231]
	v_cvt_pk_bf16_f32 v212, v54, v55
	v_cvt_pk_bf16_f32 v213, v56, v57
	v_cvt_pk_bf16_f32 v214, v50, v51
	v_cvt_pk_bf16_f32 v215, v52, v53
	global_store_dwordx4 v[228:229], v[212:215], off
	v_lshl_add_u64 v[228:229], v[228:229], 0, s[44:45]
	v_cvt_pk_bf16_f32 v216, v38, v39
	v_cvt_pk_bf16_f32 v217, v40, v41
	v_cvt_pk_bf16_f32 v218, v34, v35
	v_cvt_pk_bf16_f32 v219, v36, v37
	global_store_dwordx4 v[228:229], v[216:219], off
	v_lshl_add_u64 v[228:229], v[228:229], 0, s[44:45]
	v_cvt_pk_bf16_f32 v220, v22, v23
	v_cvt_pk_bf16_f32 v221, v24, v25
	v_cvt_pk_bf16_f32 v222, v18, v19
	v_cvt_pk_bf16_f32 v223, v20, v21
	global_store_dwordx4 v[228:229], v[220:223], off
	v_lshl_add_u64 v[228:229], v[228:229], 0, s[44:45]
	v_cvt_pk_bf16_f32 v212, v6, v7
	v_cvt_pk_bf16_f32 v213, v8, v9
	v_cvt_pk_bf16_f32 v214, v2, v3
	v_cvt_pk_bf16_f32 v215, v4, v5
	global_store_dwordx4 v[228:229], v[212:215], off
	s_nop 1
	s_branch .LBB0_221

.LBB0_398:
	s_or_b64 exec, exec, s[38:39]
	v_lshl_or_b32 v2, s8, 10, v142
	v_mov_b32_e32 v3, v0
	v_lshl_add_u64 v[2:3], v[68:69], 0, v[2:3]
	global_load_ushort v212, v[2:3], off
	global_load_ushort v213, v[2:3], off offset:1024
	global_load_ushort v214, v[2:3], off offset:2048
	global_load_ushort v215, v[2:3], off offset:3072
	v_add_u32_e32 v91, v143, v102
	ds_read_b128 v[92:95], v91 offset:12544
	ds_read_b128 v[164:167], v91 offset:13056
	ds_read_b128 v[216:219], v91 offset:13568
	ds_read_b128 v[220:223], v146 offset:12544
	ds_read_b128 v[224:227], v91 offset:14592
	ds_read_b128 v[228:231], v91 offset:15104
	ds_read_b128 v[244:247], v91 offset:15616
	ds_read_b128 v[248:251], v147 offset:12544
	v_add_u32_e32 v96, 0xf000, v138
	v_add_u32_e32 v97, 0xf400, v138
	v_add_u32_e32 v159, 0xf800, v138
	s_andn2_b64 vcc, exec, s[50:51]
	s_waitcnt lgkmcnt(7)
	v_mfma_f32_16x16x32_bf16 v[92:95], v[12:15], v[92:95], 0
	s_waitcnt lgkmcnt(6)
	v_mfma_f32_16x16x32_bf16 v[164:167], v[12:15], v[164:167], 0
	s_waitcnt lgkmcnt(5)
	v_mfma_f32_16x16x32_bf16 v[216:219], v[12:15], v[216:219], 0
	s_waitcnt lgkmcnt(4)
	v_mfma_f32_16x16x32_bf16 v[220:223], v[12:15], v[220:223], 0
	s_waitcnt lgkmcnt(3)
	v_mfma_f32_16x16x32_bf16 v[224:227], v[12:15], v[224:227], 0
	s_waitcnt lgkmcnt(2)
	v_mfma_f32_16x16x32_bf16 v[228:231], v[12:15], v[228:231], 0
	s_waitcnt lgkmcnt(1)
	v_mfma_f32_16x16x32_bf16 v[244:247], v[12:15], v[244:247], 0
	s_waitcnt lgkmcnt(0)
	v_mfma_f32_16x16x32_bf16 v[248:251], v[12:15], v[248:251], 0
	ds_write2_b32 v96, v92, v164 offset0:192 offset1:208
	ds_write2_b32 v97, v93, v165 offset0:64 offset1:80
	ds_write2_b32 v97, v94, v166 offset0:192 offset1:208
	ds_write2_b32 v159, v95, v167 offset0:64 offset1:80
	ds_write2_b32 v96, v216, v220 offset0:224 offset1:240
	ds_write2_b32 v97, v217, v221 offset0:96 offset1:112
	ds_write2_b32 v97, v218, v222 offset0:224 offset1:240
	ds_write2_b32 v159, v219, v223 offset0:96 offset1:112
	ds_write2_b32 v97, v224, v228 offset1:16
	ds_write2_b32 v97, v225, v229 offset0:128 offset1:144
	ds_write2_b32 v159, v226, v230 offset1:16
	ds_write2_b32 v159, v227, v231 offset0:128 offset1:144
	ds_write2_b32 v97, v244, v248 offset0:32 offset1:48
	ds_write2_b32 v97, v245, v249 offset0:160 offset1:176
	ds_write2_b32 v159, v246, v250 offset0:32 offset1:48
	ds_write2_b32 v159, v247, v251 offset0:160 offset1:176
	s_waitcnt lgkmcnt(0)
	ds_read2st64_b32 v[216:217], v140 offset1:1
	ds_read2st64_b32 v[218:219], v140 offset0:2 offset1:3
	ds_read2st64_b32 v[220:221], v140 offset0:4 offset1:5
	ds_read2st64_b32 v[222:223], v140 offset0:6 offset1:7
	ds_read2st64_b32 v[224:225], v140 offset0:8 offset1:9
	ds_read2st64_b32 v[226:227], v140 offset0:10 offset1:11
	ds_read2st64_b32 v[228:229], v140 offset0:12 offset1:13
	ds_read2st64_b32 v[230:231], v140 offset0:14 offset1:15
	ds_read2st64_b32 v[244:245], v140 offset0:16 offset1:17
	ds_read2st64_b32 v[246:247], v140 offset0:18 offset1:19
	ds_read2st64_b32 v[248:249], v140 offset0:20 offset1:21
	ds_read2st64_b32 v[250:251], v140 offset0:22 offset1:23
	ds_read2st64_b32 v[92:93], v140 offset0:24 offset1:25
	ds_read2st64_b32 v[94:95], v140 offset0:26 offset1:27
	ds_read2st64_b32 v[164:165], v140 offset0:28 offset1:29
	ds_read2st64_b32 v[166:167], v140 offset0:30 offset1:31
	s_waitcnt lgkmcnt(15)
	v_pk_fma_f32 v[14:15], v[64:65], v[60:61], v[216:217] op_sel:[0,1,0] op_sel_hi:[0,0,1] neg_lo:[1,0,0]
	v_pk_fma_f32 v[60:61], v[56:57], v[60:61], v[14:15] op_sel_hi:[0,1,1]
	v_cvt_pk_bf16_f32 v12, v60, v61
	ds_write_b16 v141, v12 offset:8192
	ds_write_b16_d16_hi v141, v12 offset:8320
	s_waitcnt lgkmcnt(15)
	v_pk_fma_f32 v[14:15], v[64:65], v[60:61], v[218:219] op_sel:[0,1,0] op_sel_hi:[0,0,1] neg_lo:[1,0,0]
	v_pk_fma_f32 v[60:61], v[56:57], v[60:61], v[14:15] op_sel_hi:[0,1,1]
	v_cvt_pk_bf16_f32 v13, v60, v61
	ds_write_b16 v141, v13 offset:8464
	ds_write_b16_d16_hi v141, v13 offset:8592
	s_waitcnt lgkmcnt(15)
	v_pk_fma_f32 v[14:15], v[64:65], v[60:61], v[220:221] op_sel:[0,1,0] op_sel_hi:[0,0,1] neg_lo:[1,0,0]
	v_pk_fma_f32 v[60:61], v[56:57], v[60:61], v[14:15] op_sel_hi:[0,1,1]
	v_cvt_pk_bf16_f32 v12, v60, v61
	ds_write_b16 v141, v12 offset:8736
	ds_write_b16_d16_hi v141, v12 offset:8864
	s_waitcnt lgkmcnt(15)
	v_pk_fma_f32 v[14:15], v[64:65], v[60:61], v[222:223] op_sel:[0,1,0] op_sel_hi:[0,0,1] neg_lo:[1,0,0]
	v_pk_fma_f32 v[60:61], v[56:57], v[60:61], v[14:15] op_sel_hi:[0,1,1]
	v_cvt_pk_bf16_f32 v13, v60, v61
	ds_write_b16 v141, v13 offset:9008
	ds_write_b16_d16_hi v141, v13 offset:9136
	s_waitcnt lgkmcnt(15)
	v_pk_fma_f32 v[14:15], v[64:65], v[60:61], v[224:225] op_sel:[0,1,0] op_sel_hi:[0,0,1] neg_lo:[1,0,0]
	v_pk_fma_f32 v[60:61], v[56:57], v[60:61], v[14:15] op_sel_hi:[0,1,1]
	v_cvt_pk_bf16_f32 v12, v60, v61
	ds_write_b16 v141, v12 offset:9280
	ds_write_b16_d16_hi v141, v12 offset:9408
	s_waitcnt lgkmcnt(15)
	v_pk_fma_f32 v[14:15], v[64:65], v[60:61], v[226:227] op_sel:[0,1,0] op_sel_hi:[0,0,1] neg_lo:[1,0,0]
	v_pk_fma_f32 v[60:61], v[56:57], v[60:61], v[14:15] op_sel_hi:[0,1,1]
	v_cvt_pk_bf16_f32 v13, v60, v61
	ds_write_b16 v141, v13 offset:9552
	ds_write_b16_d16_hi v141, v13 offset:9680
	s_waitcnt lgkmcnt(15)
	v_pk_fma_f32 v[14:15], v[64:65], v[60:61], v[228:229] op_sel:[0,1,0] op_sel_hi:[0,0,1] neg_lo:[1,0,0]
	v_pk_fma_f32 v[60:61], v[56:57], v[60:61], v[14:15] op_sel_hi:[0,1,1]
	v_cvt_pk_bf16_f32 v12, v60, v61
	ds_write_b16 v141, v12 offset:9824
	ds_write_b16_d16_hi v141, v12 offset:9952
	s_waitcnt lgkmcnt(15)
	v_pk_fma_f32 v[14:15], v[64:65], v[60:61], v[230:231] op_sel:[0,1,0] op_sel_hi:[0,0,1] neg_lo:[1,0,0]
	v_pk_fma_f32 v[60:61], v[56:57], v[60:61], v[14:15] op_sel_hi:[0,1,1]
	v_cvt_pk_bf16_f32 v13, v60, v61
	ds_write_b16 v141, v13 offset:10096
	ds_write_b16_d16_hi v141, v13 offset:10224
	s_waitcnt lgkmcnt(15)
	v_pk_fma_f32 v[14:15], v[64:65], v[60:61], v[244:245] op_sel:[0,1,0] op_sel_hi:[0,0,1] neg_lo:[1,0,0]
	v_pk_fma_f32 v[60:61], v[56:57], v[60:61], v[14:15] op_sel_hi:[0,1,1]
	v_cvt_pk_bf16_f32 v12, v60, v61
	ds_write_b16 v141, v12 offset:10368
	ds_write_b16_d16_hi v141, v12 offset:10496
	s_waitcnt lgkmcnt(15)
	v_pk_fma_f32 v[14:15], v[64:65], v[60:61], v[246:247] op_sel:[0,1,0] op_sel_hi:[0,0,1] neg_lo:[1,0,0]
	v_pk_fma_f32 v[60:61], v[56:57], v[60:61], v[14:15] op_sel_hi:[0,1,1]
	v_cvt_pk_bf16_f32 v13, v60, v61
	ds_write_b16 v141, v13 offset:10640
	ds_write_b16_d16_hi v141, v13 offset:10768
	s_waitcnt lgkmcnt(15)
	v_pk_fma_f32 v[14:15], v[64:65], v[60:61], v[248:249] op_sel:[0,1,0] op_sel_hi:[0,0,1] neg_lo:[1,0,0]
	v_pk_fma_f32 v[60:61], v[56:57], v[60:61], v[14:15] op_sel_hi:[0,1,1]
	v_cvt_pk_bf16_f32 v12, v60, v61
	ds_write_b16 v141, v12 offset:10912
	ds_write_b16_d16_hi v141, v12 offset:11040
	s_waitcnt lgkmcnt(15)
	v_pk_fma_f32 v[14:15], v[64:65], v[60:61], v[250:251] op_sel:[0,1,0] op_sel_hi:[0,0,1] neg_lo:[1,0,0]
	v_pk_fma_f32 v[60:61], v[56:57], v[60:61], v[14:15] op_sel_hi:[0,1,1]
	v_cvt_pk_bf16_f32 v13, v60, v61
	ds_write_b16 v141, v13 offset:11184
	ds_write_b16_d16_hi v141, v13 offset:11312
	s_waitcnt lgkmcnt(15)
	v_pk_fma_f32 v[14:15], v[64:65], v[60:61], v[92:93] op_sel:[0,1,0] op_sel_hi:[0,0,1] neg_lo:[1,0,0]
	v_pk_fma_f32 v[60:61], v[56:57], v[60:61], v[14:15] op_sel_hi:[0,1,1]
	v_cvt_pk_bf16_f32 v12, v60, v61
	ds_write_b16 v141, v12 offset:11456
	ds_write_b16_d16_hi v141, v12 offset:11584
	s_waitcnt lgkmcnt(15)
	v_pk_fma_f32 v[14:15], v[64:65], v[60:61], v[94:95] op_sel:[0,1,0] op_sel_hi:[0,0,1] neg_lo:[1,0,0]
	v_pk_fma_f32 v[60:61], v[56:57], v[60:61], v[14:15] op_sel_hi:[0,1,1]
	v_cvt_pk_bf16_f32 v13, v60, v61
	ds_write_b16 v141, v13 offset:11728
	ds_write_b16_d16_hi v141, v13 offset:11856
	s_waitcnt lgkmcnt(15)
	v_pk_fma_f32 v[14:15], v[64:65], v[60:61], v[164:165] op_sel:[0,1,0] op_sel_hi:[0,0,1] neg_lo:[1,0,0]
	v_pk_fma_f32 v[60:61], v[56:57], v[60:61], v[14:15] op_sel_hi:[0,1,1]
	v_cvt_pk_bf16_f32 v12, v60, v61
	ds_write_b16 v141, v12 offset:12000
	ds_write_b16_d16_hi v141, v12 offset:12128
	s_waitcnt lgkmcnt(15)
	v_pk_fma_f32 v[14:15], v[64:65], v[60:61], v[166:167] op_sel:[0,1,0] op_sel_hi:[0,0,1] neg_lo:[1,0,0]
	v_pk_fma_f32 v[60:61], v[56:57], v[60:61], v[14:15] op_sel_hi:[0,1,1]
	v_cvt_pk_bf16_f32 v13, v60, v61
	ds_write_b16 v141, v13 offset:12272
	ds_write_b16_d16_hi v141, v13 offset:12400
	s_waitcnt lgkmcnt(0)
	ds_read_b128 v[12:15], v144 offset:8192
	ds_read_b128 v[92:95], v145 offset:16640
	ds_read_b128 v[216:219], v144 offset:8256
	ds_read_b128 v[220:223], v145 offset:16704
	ds_read_b128 v[224:227], v144 offset:8320
	ds_read_b128 v[228:231], v145 offset:16768
	ds_read_b128 v[244:247], v144 offset:8384
	ds_read_b128 v[248:251], v145 offset:16832
	s_waitcnt lgkmcnt(6)
	v_mfma_f32_16x16x32_bf16 v[12:15], v[12:15], v[92:95], 0
	s_waitcnt lgkmcnt(4)
	v_mfma_f32_16x16x32_bf16 v[12:15], v[216:219], v[220:223], v[12:15]
	s_waitcnt lgkmcnt(2)
	v_mfma_f32_16x16x32_bf16 v[12:15], v[224:227], v[228:231], v[12:15]
	s_waitcnt lgkmcnt(0)
	v_mfma_f32_16x16x32_bf16 v[12:15], v[244:247], v[248:251], v[12:15]
	s_nop 7
	s_waitcnt vmcnt(0)
	v_lshlrev_b32_e32 v88, 16, v212
	v_lshlrev_b32_e32 v89, 16, v213
	v_lshlrev_b32_e32 v90, 16, v214
	v_lshlrev_b32_e32 v91, 16, v215
	v_pk_fma_f32 v[12:13], v[148:149], v[88:89], v[12:13] op_sel_hi:[0,1,1]
	v_pk_fma_f32 v[14:15], v[148:149], v[90:91], v[14:15] op_sel_hi:[0,1,1]
	v_mov_b32_e32 v88, 0x3dd2d3e8
	v_mov_b32_e32 v90, 0x40135761
	v_pk_mul_f32 v[92:93], v[12:13], v[12:13]
	v_pk_mul_f32 v[94:95], v[14:15], v[14:15]
	v_pk_fma_f32 v[92:93], v[92:93], v[88:89], v[90:91] op_sel_hi:[1,0,0]
	v_pk_fma_f32 v[94:95], v[94:95], v[88:89], v[90:91] op_sel_hi:[1,0,0]
	v_pk_mul_f32 v[92:93], v[92:93], v[12:13]
	v_pk_mul_f32 v[94:95], v[94:95], v[14:15]
	v_mov_b32_e32 v88, 1.0
	v_exp_f32_e32 v92, v92
	v_exp_f32_e32 v93, v93
	v_exp_f32_e32 v94, v94
	v_exp_f32_e32 v95, v95
	s_nop 0
	v_pk_add_f32 v[92:93], v[92:93], v[88:89] op_sel_hi:[1,0]
	v_pk_add_f32 v[94:95], v[94:95], v[88:89] op_sel_hi:[1,0]
	v_rcp_f32_e32 v92, v92
	v_rcp_f32_e32 v93, v93
	v_rcp_f32_e32 v94, v94
	v_rcp_f32_e32 v95, v95
	s_nop 0
	v_pk_fma_f32 v[12:13], v[12:13], v[92:93], v[12:13] neg_lo:[1,0,0] neg_hi:[1,0,0]
	v_pk_fma_f32 v[14:15], v[14:15], v[94:95], v[14:15] neg_lo:[1,0,0] neg_hi:[1,0,0]
	v_cvt_pk_bf16_f32 v12, v12, v13
	v_cvt_pk_bf16_f32 v14, v14, v15
	global_store_short v[2:3], v12, off
	global_store_short_d16_hi v[2:3], v12, off offset:1024
	global_store_short v[2:3], v14, off offset:2048
	global_store_short_d16_hi v[2:3], v14, off offset:3072
	s_waitcnt lgkmcnt(0)
	v_lshlrev_b32_e32 v1, 2, v128
	s_cbranch_vccnz .LBB0_408
	s_waitcnt vmcnt(4)
	v_lshlrev_b32_e32 v16, 16, v176
	v_lshlrev_b32_e32 v30, 16, v177
	v_lshlrev_b32_e32 v32, 16, v178
	v_lshlrev_b32_e32 v36, 16, v179
	v_lshlrev_b32_e32 v17, 16, v180
	v_lshlrev_b32_e32 v26, 16, v181
	v_lshlrev_b32_e32 v27, 16, v182
	v_lshlrev_b32_e32 v28, 16, v183
	v_lshlrev_b32_e32 v29, 16, v184
	v_lshlrev_b32_e32 v31, 16, v185
	v_lshlrev_b32_e32 v33, 16, v186
	v_lshlrev_b32_e32 v37, 16, v187
	v_lshlrev_b32_e32 v34, 16, v188
	v_lshlrev_b32_e32 v35, 16, v189
	v_lshlrev_b32_e32 v38, 16, v190
	v_lshlrev_b32_e32 v39, 16, v195
	v_lshlrev_b32_e32 v40, 16, v197
	v_lshlrev_b32_e32 v43, 16, v198
	v_lshlrev_b32_e32 v42, 16, v199
	v_lshlrev_b32_e32 v45, 16, v200
	v_lshlrev_b32_e32 v44, 16, v201
	v_lshlrev_b32_e32 v46, 16, v203
	v_lshlrev_b32_e32 v49, 16, v204
	v_lshlrev_b32_e32 v48, 16, v205
	v_lshlrev_b32_e32 v41, 16, v196
	v_lshlrev_b32_e32 v47, 16, v202
	v_lshlrev_b32_e32 v51, 16, v206
	v_lshlrev_b32_e32 v50, 16, v207
	v_lshlrev_b32_e32 v53, 16, v191
	v_lshlrev_b32_e32 v52, 16, v193
	v_lshlrev_b32_e32 v55, 16, v192
	v_lshlrev_b32_e32 v54, 16, v194
	v_add_f32_e32 v88, v155, v35
	v_mul_f32_e32 v88, 0xbfb8aa3b, v88
	v_exp_f32_e32 v88, v88
	v_pk_add_f32 v[12:13], v[32:33], v[26:27] neg_lo:[0,1] neg_hi:[0,1]
	v_pk_add_f32 v[2:3], v[30:31], v[16:17] neg_lo:[0,1] neg_hi:[0,1]
	v_fma_f32 v13, v150, v13, v27
	v_add_f32_e32 v88, 1.0, v88
	v_rcp_f32_e32 v88, v88
	v_mul_f32_e32 v92, v157, v13
	v_fma_f32 v3, v149, v3, v17
	s_bitcmp1_b32 s3, 0
	v_mul_f32_e32 v89, 0xbf6002b1, v88
	v_cmp_gt_f32_e32 vcc, s85, v89
	s_cselect_b32 s8, 0x5000, 0
	v_mov_b32_e32 v94, v0
	v_cndmask_b32_e32 v89, 0, v239, vcc
	v_fmac_f32_e32 v89, 0xbf6002b1, v88
	v_exp_f32_e32 v88, v89
	v_cndmask_b32_e32 v89, 0, v236, vcc
	s_add_i32 s9, s8, 0
	s_mul_i32 s8, s3, 0xab
	v_ldexp_f32 v90, v88, v89
	v_add_f32_e32 v88, v154, v39
	v_mul_f32_e32 v88, 0xbfb8aa3b, v88
	v_exp_f32_e32 v88, v88
	v_mov_b32_e32 v89, v0
	s_bfe_u32 s8, s8, 0x70009
	s_mul_i32 s8, s8, 3
	v_add_f32_e32 v88, 1.0, v88
	v_rcp_f32_e32 v91, v88
	v_mul_f32_e32 v88, v92, v92
	s_sub_i32 s8, s3, s8
	s_and_b32 s8, s8, 0xff
	v_mov_b32_dpp v89, v88 quad_perm:[1,0,3,2] row_mask:0xf bank_mask:0xf
	v_fmac_f32_e32 v89, v92, v92
	s_mulk_i32 s8, 0x1100
	s_add_i32 s8, s8, 0
	v_add_f32_dpp v88, v89, v89 quad_perm:[2,3,0,1] row_mask:0xf bank_mask:0xf bound_ctrl:1
	v_pk_add_f32 v[14:15], v[36:37], v[28:29] neg_lo:[0,1] neg_hi:[0,1]
	s_nop 0
	v_add_f32_dpp v88, v88, v88 row_half_mirror row_mask:0xf bank_mask:0xf bound_ctrl:1
	v_fma_f32 v15, v151, v15, v29
	s_nop 0
	v_add_f32_dpp v88, v88, v88 row_mirror row_mask:0xf bank_mask:0xf bound_ctrl:1
	s_nop 0
	s_nop 1
	v_add_f32_dpp v88, v88, v88 row_bcast:15 row_mask:0xa bank_mask:0xf
	s_nop 1
	v_add_f32_dpp v88, v88, v88 row_bcast:31 row_mask:0xc bank_mask:0xf
	s_nop 0
	v_readlane_b32 s26, v88, 63
	v_mov_b32_e32 v88, s26
	v_add_f32_e32 v88, 0x2b8cbccc, v88
	v_cmp_gt_f32_e32 vcc, s82, v88
	v_mul_f32_e32 v89, 0x4b800000, v88
	s_nop 0
	v_cndmask_b32_e32 v88, v88, v89, vcc
	v_rsq_f32_e32 v88, v88
	s_nop 0
	v_mul_f32_e32 v89, 0x45800000, v88
	v_cndmask_b32_e32 v88, v88, v89, vcc
	v_add_f32_e32 v89, -1.0, v91
	v_fma_f32 v89, v158, v89, 1.0
	v_mul_f32_e32 v13, v89, v13
	v_mul_f32_e32 v89, v13, v3
	v_mul_f32_e32 v93, v156, v89
	v_mul_f32_e64 v88, v92, -v88
	s_nop 0
	v_mov_b32_dpp v94, v93 quad_perm:[1,0,3,2] row_mask:0xf bank_mask:0xf
	v_fmac_f32_e32 v94, v156, v89
	s_nop 1
	v_add_f32_dpp v89, v94, v94 quad_perm:[2,3,0,1] row_mask:0xf bank_mask:0xf bound_ctrl:1
	s_nop 1
	v_add_f32_dpp v89, v89, v89 row_half_mirror row_mask:0xf bank_mask:0xf bound_ctrl:1
	s_nop 1
	v_add_f32_dpp v89, v89, v89 row_mirror row_mask:0xf bank_mask:0xf bound_ctrl:1
	s_nop 0
	s_nop 1
	v_add_f32_dpp v89, v89, v89 row_bcast:15 row_mask:0xa bank_mask:0xf
	s_nop 1
	v_add_f32_dpp v89, v89, v89 row_bcast:31 row_mask:0xc bank_mask:0xf
	s_nop 0
	v_readlane_b32 s38, v89, 63
	v_add_u32_e32 v89, s9, v1
	ds_write2st64_b32 v89, v90, v88 offset1:16
	v_mul_f32_e64 v88, v91, -v88
	ds_write2st64_b32 v89, v88, v13 offset0:32 offset1:48
	ds_write_b32 v89, v3 offset:16384
	v_add_u32_e32 v3, s8, v1
	ds_write_b32 v3, v15 offset:40960
	s_and_saveexec_b64 s[50:51], s[44:45]
	s_cbranch_execz .LBB0_401
	s_lshl_b32 s24, s96, 2
	s_add_i32 s24, s8, s24
	v_mov_b32_e32 v13, s24
	v_mov_b32_e32 v3, s38
	ds_write_b32 v13, v3 offset:45056
.LBB0_401:
	s_or_b64 exec, exec, s[50:51]
	v_fma_f32 v13, v149, v2, v16
	v_add_f32_e32 v2, v155, v34
	v_mul_f32_e32 v2, 0xbfb8aa3b, v2
	v_exp_f32_e32 v2, v2
	v_fma_f32 v12, v150, v12, v26
	v_mul_f32_e32 v89, v157, v12
	v_mov_b32_e32 v91, v0
	v_add_f32_e32 v2, 1.0, v2
	v_rcp_f32_e32 v2, v2
	v_fma_f32 v14, v151, v14, v28
	v_mul_f32_e32 v3, 0xbf6002b1, v2
	v_cmp_gt_f32_e32 vcc, s85, v3
	s_nop 1
	v_cndmask_b32_e32 v3, 0, v239, vcc
	v_fmac_f32_e32 v3, 0xbf6002b1, v2
	v_exp_f32_e32 v2, v3
	v_cndmask_b32_e32 v3, 0, v236, vcc
	v_ldexp_f32 v15, v2, v3
	v_add_f32_e32 v2, v154, v38
	v_mul_f32_e32 v2, 0xbfb8aa3b, v2
	v_exp_f32_e32 v2, v2
	v_mov_b32_e32 v3, v0
	v_add_f32_e32 v2, 1.0, v2
	v_rcp_f32_e32 v88, v2
	v_mul_f32_e32 v2, v89, v89
	s_nop 1
	v_mov_b32_dpp v3, v2 quad_perm:[1,0,3,2] row_mask:0xf bank_mask:0xf
	v_fmac_f32_e32 v3, v89, v89
	s_nop 1
	v_add_f32_dpp v2, v3, v3 quad_perm:[2,3,0,1] row_mask:0xf bank_mask:0xf bound_ctrl:1
	s_nop 1
	v_add_f32_dpp v2, v2, v2 row_half_mirror row_mask:0xf bank_mask:0xf bound_ctrl:1
	s_nop 1
	v_add_f32_dpp v2, v2, v2 row_mirror row_mask:0xf bank_mask:0xf bound_ctrl:1
	s_nop 0
	s_nop 1
	v_add_f32_dpp v2, v2, v2 row_bcast:15 row_mask:0xa bank_mask:0xf
	s_nop 1
	v_add_f32_dpp v2, v2, v2 row_bcast:31 row_mask:0xc bank_mask:0xf
	s_nop 0
	v_readlane_b32 s26, v2, 63
	v_mov_b32_e32 v2, s26
	v_add_f32_e32 v2, 0x2b8cbccc, v2
	v_cmp_gt_f32_e32 vcc, s82, v2
	v_mul_f32_e32 v3, 0x4b800000, v2
	s_nop 0
	v_cndmask_b32_e32 v2, v2, v3, vcc
	v_rsq_f32_e32 v2, v2
	s_nop 0
	v_mul_f32_e32 v3, 0x45800000, v2
	v_cndmask_b32_e32 v2, v2, v3, vcc
	v_add_f32_e32 v3, -1.0, v88
	v_fma_f32 v3, v158, v3, 1.0
	v_mul_f32_e32 v3, v3, v12
	v_mul_f32_e32 v12, v3, v13
	v_mul_f32_e32 v90, v156, v12
	v_mul_f32_e64 v2, v89, -v2
	s_nop 0
	v_mov_b32_dpp v91, v90 quad_perm:[1,0,3,2] row_mask:0xf bank_mask:0xf
	v_fmac_f32_e32 v91, v156, v12
	s_nop 1
	v_add_f32_dpp v12, v91, v91 quad_perm:[2,3,0,1] row_mask:0xf bank_mask:0xf bound_ctrl:1
	s_nop 1
	v_add_f32_dpp v12, v12, v12 row_half_mirror row_mask:0xf bank_mask:0xf bound_ctrl:1
	s_nop 1
	v_add_f32_dpp v12, v12, v12 row_mirror row_mask:0xf bank_mask:0xf bound_ctrl:1
	s_nop 0
	s_nop 1
	v_add_f32_dpp v12, v12, v12 row_bcast:15 row_mask:0xa bank_mask:0xf
	s_nop 1
	v_add_f32_dpp v12, v12, v12 row_bcast:31 row_mask:0xc bank_mask:0xf
	s_nop 0
	v_readlane_b32 s38, v12, 63
	v_lshlrev_b32_e32 v12, 2, v130
	v_add_u32_e32 v90, s9, v12
	ds_write2st64_b32 v90, v15, v2 offset1:16
	v_mul_f32_e64 v2, v88, -v2
	ds_write2st64_b32 v90, v2, v3 offset0:32 offset1:48
	ds_write_b32 v90, v13 offset:16384
	v_add_u32_e32 v2, s8, v12
	ds_write_b32 v2, v14 offset:40960
	s_and_saveexec_b64 s[50:51], s[44:45]
	s_cbranch_execz .LBB0_403
	s_lshl_b32 s24, s96, 2
	s_add_i32 s24, s8, s24
	s_nop 0
	v_mov_b32_e32 v2, s38
	v_mov_b32_e32 v3, s24
	ds_write_b32 v3, v2 offset:45072
.LBB0_403:
	s_or_b64 exec, exec, s[50:51]
	v_add_f32_e32 v88, v155, v53
	v_mul_f32_e32 v88, 0xbfb8aa3b, v88
	v_exp_f32_e32 v88, v88
	v_pk_add_f32 v[12:13], v[48:49], v[42:43] neg_lo:[0,1] neg_hi:[0,1]
	v_pk_add_f32 v[2:3], v[46:47], v[40:41] neg_lo:[0,1] neg_hi:[0,1]
	v_fma_f32 v13, v150, v13, v43
	v_add_f32_e32 v88, 1.0, v88
	v_rcp_f32_e32 v88, v88
	v_mul_f32_e32 v92, v157, v13
	v_fma_f32 v3, v149, v3, v41
	v_mov_b32_e32 v94, v0
	v_mul_f32_e32 v89, 0xbf6002b1, v88
	v_cmp_gt_f32_e32 vcc, s85, v89
	v_pk_add_f32 v[14:15], v[50:51], v[44:45] neg_lo:[0,1] neg_hi:[0,1]
	s_nop 0
	v_cndmask_b32_e32 v89, 0, v239, vcc
	v_fmac_f32_e32 v89, 0xbf6002b1, v88
	v_exp_f32_e32 v88, v89
	v_cndmask_b32_e32 v89, 0, v236, vcc
	v_fma_f32 v15, v151, v15, v45
	v_ldexp_f32 v90, v88, v89
	v_add_f32_e32 v88, v154, v55
	v_mul_f32_e32 v88, 0xbfb8aa3b, v88
	v_exp_f32_e32 v88, v88
	v_mov_b32_e32 v89, v0
	v_add_f32_e32 v88, 1.0, v88
	v_rcp_f32_e32 v91, v88
	v_mul_f32_e32 v88, v92, v92
	s_nop 1
	v_mov_b32_dpp v89, v88 quad_perm:[1,0,3,2] row_mask:0xf bank_mask:0xf
	v_fmac_f32_e32 v89, v92, v92
	s_nop 1
	v_add_f32_dpp v88, v89, v89 quad_perm:[2,3,0,1] row_mask:0xf bank_mask:0xf bound_ctrl:1
	s_nop 1
	v_add_f32_dpp v88, v88, v88 row_half_mirror row_mask:0xf bank_mask:0xf bound_ctrl:1
	s_nop 1
	v_add_f32_dpp v88, v88, v88 row_mirror row_mask:0xf bank_mask:0xf bound_ctrl:1
	s_nop 0
	s_nop 1
	v_add_f32_dpp v88, v88, v88 row_bcast:15 row_mask:0xa bank_mask:0xf
	s_nop 1
	v_add_f32_dpp v88, v88, v88 row_bcast:31 row_mask:0xc bank_mask:0xf
	s_nop 0
	v_readlane_b32 s26, v88, 63
	v_mov_b32_e32 v88, s26
	v_add_f32_e32 v88, 0x2b8cbccc, v88
	v_cmp_gt_f32_e32 vcc, s82, v88
	v_mul_f32_e32 v89, 0x4b800000, v88
	s_nop 0
	v_cndmask_b32_e32 v88, v88, v89, vcc
	v_rsq_f32_e32 v88, v88
	s_nop 0
	v_mul_f32_e32 v89, 0x45800000, v88
	v_cndmask_b32_e32 v88, v88, v89, vcc
	v_add_f32_e32 v89, -1.0, v91
	v_fma_f32 v89, v158, v89, 1.0
	v_mul_f32_e32 v13, v89, v13
	v_mul_f32_e32 v89, v13, v3
	v_mul_f32_e32 v93, v156, v89
	v_mul_f32_e64 v88, v92, -v88
	s_nop 0
	v_mov_b32_dpp v94, v93 quad_perm:[1,0,3,2] row_mask:0xf bank_mask:0xf
	v_fmac_f32_e32 v94, v156, v89
	s_nop 1
	v_add_f32_dpp v89, v94, v94 quad_perm:[2,3,0,1] row_mask:0xf bank_mask:0xf bound_ctrl:1
	s_nop 1
	v_add_f32_dpp v89, v89, v89 row_half_mirror row_mask:0xf bank_mask:0xf bound_ctrl:1
	s_nop 1
	v_add_f32_dpp v89, v89, v89 row_mirror row_mask:0xf bank_mask:0xf bound_ctrl:1
	s_nop 0
	s_nop 1
	v_add_f32_dpp v89, v89, v89 row_bcast:15 row_mask:0xa bank_mask:0xf
	s_nop 1
	v_add_f32_dpp v89, v89, v89 row_bcast:31 row_mask:0xc bank_mask:0xf
	s_nop 0
	v_readlane_b32 s38, v89, 63
	v_lshlrev_b32_e32 v89, 2, v132
	v_add_u32_e32 v93, s9, v89
	ds_write2st64_b32 v93, v90, v88 offset1:16
	v_mul_f32_e64 v88, v91, -v88
	ds_write2st64_b32 v93, v88, v13 offset0:32 offset1:48
	ds_write_b32 v93, v3 offset:16384
	v_add_u32_e32 v3, s8, v89
	ds_write_b32 v3, v15 offset:40960
	s_and_saveexec_b64 s[50:51], s[44:45]
	s_cbranch_execz .LBB0_405
	s_lshl_b32 s24, s96, 2
	s_add_i32 s24, s8, s24
	v_mov_b32_e32 v13, s24
	v_mov_b32_e32 v3, s38
	ds_write_b32 v13, v3 offset:45088
.LBB0_405:
	s_or_b64 exec, exec, s[50:51]
	v_fma_f32 v13, v149, v2, v40
	v_add_f32_e32 v2, v155, v52
	v_mul_f32_e32 v2, 0xbfb8aa3b, v2
	v_exp_f32_e32 v2, v2
	v_fma_f32 v12, v150, v12, v42
	v_mul_f32_e32 v89, v157, v12
	v_mov_b32_e32 v91, v0
	v_add_f32_e32 v2, 1.0, v2
	v_rcp_f32_e32 v2, v2
	v_fma_f32 v14, v151, v14, v44
	v_mul_f32_e32 v3, 0xbf6002b1, v2
	v_cmp_gt_f32_e32 vcc, s85, v3
	s_nop 1
	v_cndmask_b32_e32 v3, 0, v239, vcc
	v_fmac_f32_e32 v3, 0xbf6002b1, v2
	v_exp_f32_e32 v2, v3
	v_cndmask_b32_e32 v3, 0, v236, vcc
	v_ldexp_f32 v15, v2, v3
	v_add_f32_e32 v2, v154, v54
	v_mul_f32_e32 v2, 0xbfb8aa3b, v2
	v_exp_f32_e32 v2, v2
	v_mov_b32_e32 v3, v0
	v_add_f32_e32 v2, 1.0, v2
	v_rcp_f32_e32 v88, v2
	v_mul_f32_e32 v2, v89, v89
	s_nop 1
	v_mov_b32_dpp v3, v2 quad_perm:[1,0,3,2] row_mask:0xf bank_mask:0xf
	v_fmac_f32_e32 v3, v89, v89
	s_nop 1
	v_add_f32_dpp v2, v3, v3 quad_perm:[2,3,0,1] row_mask:0xf bank_mask:0xf bound_ctrl:1
	s_nop 1
	v_add_f32_dpp v2, v2, v2 row_half_mirror row_mask:0xf bank_mask:0xf bound_ctrl:1
	s_nop 1
	v_add_f32_dpp v2, v2, v2 row_mirror row_mask:0xf bank_mask:0xf bound_ctrl:1
	s_nop 0
	s_nop 1
	v_add_f32_dpp v2, v2, v2 row_bcast:15 row_mask:0xa bank_mask:0xf
	s_nop 1
	v_add_f32_dpp v2, v2, v2 row_bcast:31 row_mask:0xc bank_mask:0xf
	s_nop 0
	v_readlane_b32 s26, v2, 63
	v_mov_b32_e32 v2, s26
	v_add_f32_e32 v2, 0x2b8cbccc, v2
	v_cmp_gt_f32_e32 vcc, s82, v2
	v_mul_f32_e32 v3, 0x4b800000, v2
	s_nop 0
	v_cndmask_b32_e32 v2, v2, v3, vcc
	v_rsq_f32_e32 v2, v2
	s_nop 0
	v_mul_f32_e32 v3, 0x45800000, v2
	v_cndmask_b32_e32 v2, v2, v3, vcc
	v_add_f32_e32 v3, -1.0, v88
	v_fma_f32 v3, v158, v3, 1.0
	v_mul_f32_e32 v3, v3, v12
	v_mul_f32_e32 v12, v3, v13
	v_mul_f32_e32 v90, v156, v12
	v_mul_f32_e64 v2, v89, -v2
	s_nop 0
	v_mov_b32_dpp v91, v90 quad_perm:[1,0,3,2] row_mask:0xf bank_mask:0xf
	v_fmac_f32_e32 v91, v156, v12
	s_nop 1
	v_add_f32_dpp v12, v91, v91 quad_perm:[2,3,0,1] row_mask:0xf bank_mask:0xf bound_ctrl:1
	s_nop 1
	v_add_f32_dpp v12, v12, v12 row_half_mirror row_mask:0xf bank_mask:0xf bound_ctrl:1
	s_nop 1
	v_add_f32_dpp v12, v12, v12 row_mirror row_mask:0xf bank_mask:0xf bound_ctrl:1
	s_nop 0
	s_nop 1
	v_add_f32_dpp v12, v12, v12 row_bcast:15 row_mask:0xa bank_mask:0xf
	s_nop 1
	v_add_f32_dpp v12, v12, v12 row_bcast:31 row_mask:0xc bank_mask:0xf
	s_nop 0
	v_readlane_b32 s38, v12, 63
	v_lshlrev_b32_e32 v12, 2, v134
	v_add_u32_e32 v90, s9, v12
	ds_write2st64_b32 v90, v15, v2 offset1:16
	v_mul_f32_e64 v2, v88, -v2
	ds_write2st64_b32 v90, v2, v3 offset0:32 offset1:48
	ds_write_b32 v90, v13 offset:16384
	v_add_u32_e32 v2, s8, v12
	ds_write_b32 v2, v14 offset:40960
	s_and_saveexec_b64 s[50:51], s[44:45]
	s_cbranch_execz .LBB0_407
	s_lshl_b32 s9, s96, 2
	s_add_i32 s8, s8, s9
	s_nop 0
	v_mov_b32_e32 v2, s38
	v_mov_b32_e32 v3, s8
	ds_write_b32 v3, v2 offset:45104

.LBB0_408:
	s_andn2_b64 vcc, exec, s[36:37]
	s_mov_b32 s8, 1
	s_cbranch_vccnz .LBB0_410
	s_waitcnt vmcnt(4)
	v_lshlrev_b32_e32 v4, 16, v208
	v_lshlrev_b32_e32 v5, 16, v209
	v_lshlrev_b32_e32 v6, 16, v210
	v_lshlrev_b32_e32 v7, 16, v211
	s_add_i32 s8, s2, -1
	s_and_b32 s2, s8, 0xff
	s_mulk_i32 s2, 0xab
	s_lshr_b32 s2, s2, 9
	s_mul_i32 s2, s2, 3
	s_sub_i32 s2, s8, s2
	s_and_b32 s2, s2, 0xff
	s_lshl_b32 s9, s8, 12
	s_mulk_i32 s2, 0x1100
	s_and_b32 s9, s9, 0x1000
	s_add_i32 s2, s2, 0
	s_add_i32 s9, s9, 0
	v_lshlrev_b32_e32 v15, 2, v134
	v_add_u32_e32 v2, s9, v1
	v_add_u32_e32 v1, s2, v1
	v_lshlrev_b32_e32 v3, 2, v130
	v_lshlrev_b32_e32 v13, 2, v132
	v_add_u32_e32 v88, s9, v15
	v_add_u32_e32 v12, s9, v3
	v_add_u32_e32 v3, s2, v3
	v_add_u32_e32 v14, s9, v13
	v_add_u32_e32 v13, s2, v13
	v_add_u32_e32 v15, s2, v15
	ds_read_b32 v89, v2 offset:54016
	ds_read_b32 v1, v1 offset:40960
	ds_read_b32 v90, v12 offset:54016
	ds_read_b32 v91, v3 offset:40960
	ds_read_b32 v92, v14 offset:54016
	ds_read_b32 v93, v13 offset:40960
	ds_read_b32 v88, v88 offset:54016
	ds_read_b32 v94, v15 offset:40960
	s_waitcnt lgkmcnt(7)
	v_add_f32_dpp v2, v89, v89 quad_perm:[1,0,3,2] row_mask:0xf bank_mask:0xf bound_ctrl:1
	s_lshl_b32 s8, s8, 4
	s_add_u32 s36, s30, s8
	v_add_f32_dpp v2, v2, v2 quad_perm:[2,3,0,1] row_mask:0xf bank_mask:0xf bound_ctrl:1
	s_addc_u32 s37, s31, 0
	s_nop 0
	v_add_f32_dpp v2, v2, v2 row_half_mirror row_mask:0xf bank_mask:0xf bound_ctrl:1
	s_nop 1
	v_add_f32_dpp v2, v2, v2 row_mirror row_mask:0xf bank_mask:0xf bound_ctrl:1
	s_nop 0
	s_nop 1
	v_add_f32_dpp v2, v2, v2 row_bcast:15 row_mask:0xa bank_mask:0xf
	s_nop 1
	v_add_f32_dpp v2, v2, v2 row_bcast:31 row_mask:0xc bank_mask:0xf
	s_nop 0
	v_readlane_b32 s9, v2, 63
	v_mov_b32_e32 v2, s9
	v_fmac_f32_e32 v89, 0xbc800000, v2
	v_mul_f32_e32 v2, v89, v89
	v_mov_b32_e32 v3, v0
	s_nop 1
	v_mov_b32_dpp v3, v2 quad_perm:[1,0,3,2] row_mask:0xf bank_mask:0xf
	v_fmac_f32_e32 v3, v89, v89
	s_nop 1
	v_add_f32_dpp v2, v3, v3 quad_perm:[2,3,0,1] row_mask:0xf bank_mask:0xf bound_ctrl:1
	s_nop 1
	v_add_f32_dpp v2, v2, v2 row_half_mirror row_mask:0xf bank_mask:0xf bound_ctrl:1
	s_nop 1
	v_add_f32_dpp v2, v2, v2 row_mirror row_mask:0xf bank_mask:0xf bound_ctrl:1
	s_nop 0
	s_lshl_b32 s24, s96, 2
	s_nop 1
	v_add_f32_dpp v2, v2, v2 row_bcast:15 row_mask:0xa bank_mask:0xf
	s_nop 1
	v_add_f32_dpp v2, v2, v2 row_bcast:31 row_mask:0xc bank_mask:0xf
	s_nop 0
	v_readlane_b32 s9, v2, 63
	v_mov_b32_e32 v2, s9
	v_fmamk_f32 v2, v2, 0x3c800000, v233
	v_mul_f32_e32 v3, 0x4b800000, v2
	v_cmp_gt_f32_e32 vcc, s82, v2
	s_add_i32 s2, s2, s24
	s_or_b64 s[8:9], s[36:37], s[96:97]
	v_cndmask_b32_e32 v2, v2, v3, vcc
	v_rsq_f32_e32 v12, v2
	v_mov_b32_e32 v2, s2
	v_add_u32_e32 v14, 0xb000, v2
	ds_read2_b32 v[2:3], v14 offset1:4
	v_mul_f32_e32 v13, 0x45800000, v12
	v_cndmask_b32_e32 v12, v12, v13, vcc
	v_mul_f32_e32 v12, v89, v12
	v_fma_f32 v15, v153, v12, v152
	s_waitcnt lgkmcnt(0)
	v_fmac_f32_e32 v15, v2, v1
	v_add_f32_dpp v2, v90, v90 quad_perm:[1,0,3,2] row_mask:0xf bank_mask:0xf bound_ctrl:1
	ds_read2_b32 v[12:13], v14 offset0:8 offset1:12
	v_mul_f32_e32 v1, v4, v15
	v_add_f32_dpp v2, v2, v2 quad_perm:[2,3,0,1] row_mask:0xf bank_mask:0xf bound_ctrl:1
	s_lshl_b64 s[8:9], s[8:9], 10
	v_cvt_pk_bf16_f32 v1, v1, v0
	s_nop 0
	v_add_f32_dpp v2, v2, v2 row_half_mirror row_mask:0xf bank_mask:0xf bound_ctrl:1
	s_nop 1
	v_add_f32_dpp v2, v2, v2 row_mirror row_mask:0xf bank_mask:0xf bound_ctrl:1
	s_nop 0
	s_nop 1
	v_add_f32_dpp v2, v2, v2 row_bcast:15 row_mask:0xa bank_mask:0xf
	s_nop 1
	v_add_f32_dpp v2, v2, v2 row_bcast:31 row_mask:0xc bank_mask:0xf
	s_nop 0
	v_readlane_b32 s2, v2, 63
	v_mov_b32_e32 v2, s2
	v_fmac_f32_e32 v90, 0xbc800000, v2
	v_mul_f32_e32 v2, v90, v90
	v_mov_b32_e32 v14, v0
	s_nop 1
	v_mov_b32_dpp v14, v2 quad_perm:[1,0,3,2] row_mask:0xf bank_mask:0xf
	v_fmac_f32_e32 v14, v90, v90
	s_nop 1
	v_add_f32_dpp v2, v14, v14 quad_perm:[2,3,0,1] row_mask:0xf bank_mask:0xf bound_ctrl:1
	s_nop 1
	v_add_f32_dpp v2, v2, v2 row_half_mirror row_mask:0xf bank_mask:0xf bound_ctrl:1
	s_nop 1
	v_add_f32_dpp v2, v2, v2 row_mirror row_mask:0xf bank_mask:0xf bound_ctrl:1
	s_nop 0
	s_nop 1
	v_add_f32_dpp v2, v2, v2 row_bcast:15 row_mask:0xa bank_mask:0xf
	s_nop 1
	v_add_f32_dpp v2, v2, v2 row_bcast:31 row_mask:0xc bank_mask:0xf
	s_nop 0
	v_readlane_b32 s2, v2, 63
	v_mov_b32_e32 v2, s2
	v_fmamk_f32 v2, v2, 0x3c800000, v233
	v_mul_f32_e32 v14, 0x4b800000, v2
	v_cmp_gt_f32_e32 vcc, s82, v2
	s_nop 1
	v_cndmask_b32_e32 v2, v2, v14, vcc
	v_rsq_f32_e32 v2, v2
	v_lshl_add_u64 v[14:15], v[58:59], 0, s[8:9]
	global_store_short v[14:15], v1, off
	s_or_b64 s[8:9], s[36:37], s[12:13]
	v_mul_f32_e32 v1, 0x45800000, v2
	v_cndmask_b32_e32 v1, v2, v1, vcc
	v_add_f32_dpp v2, v92, v92 quad_perm:[1,0,3,2] row_mask:0xf bank_mask:0xf bound_ctrl:1
	v_mul_f32_e32 v1, v90, v1
	v_fma_f32 v1, v153, v1, v152
	v_add_f32_dpp v2, v2, v2 quad_perm:[2,3,0,1] row_mask:0xf bank_mask:0xf bound_ctrl:1
	v_fmac_f32_e32 v1, v3, v91
	s_lshl_b64 s[8:9], s[8:9], 10
	v_add_f32_dpp v2, v2, v2 row_half_mirror row_mask:0xf bank_mask:0xf bound_ctrl:1
	v_mul_f32_e32 v1, v5, v1
	v_cvt_pk_bf16_f32 v1, v1, v0
	s_nop 0
	v_add_f32_dpp v2, v2, v2 row_mirror row_mask:0xf bank_mask:0xf bound_ctrl:1
	s_nop 0
	s_nop 1
	v_add_f32_dpp v2, v2, v2 row_bcast:15 row_mask:0xa bank_mask:0xf
	s_nop 1
	v_add_f32_dpp v2, v2, v2 row_bcast:31 row_mask:0xc bank_mask:0xf
	s_nop 0
	v_readlane_b32 s2, v2, 63
	v_mov_b32_e32 v2, s2
	v_fmac_f32_e32 v92, 0xbc800000, v2
	v_mul_f32_e32 v2, v92, v92
	v_mov_b32_e32 v3, v0
	s_nop 1
	v_mov_b32_dpp v3, v2 quad_perm:[1,0,3,2] row_mask:0xf bank_mask:0xf
	v_fmac_f32_e32 v3, v92, v92
	s_nop 1
	v_add_f32_dpp v2, v3, v3 quad_perm:[2,3,0,1] row_mask:0xf bank_mask:0xf bound_ctrl:1
	s_nop 1
	v_add_f32_dpp v2, v2, v2 row_half_mirror row_mask:0xf bank_mask:0xf bound_ctrl:1
	s_nop 1
	v_add_f32_dpp v2, v2, v2 row_mirror row_mask:0xf bank_mask:0xf bound_ctrl:1
	s_nop 0
	s_nop 1
	v_add_f32_dpp v2, v2, v2 row_bcast:15 row_mask:0xa bank_mask:0xf
	s_nop 1
	v_add_f32_dpp v2, v2, v2 row_bcast:31 row_mask:0xc bank_mask:0xf
	s_nop 0
	v_readlane_b32 s2, v2, 63
	v_mov_b32_e32 v2, s2
	v_fmamk_f32 v2, v2, 0x3c800000, v233
	v_mul_f32_e32 v3, 0x4b800000, v2
	v_cmp_gt_f32_e32 vcc, s82, v2
	s_nop 1
	v_cndmask_b32_e32 v2, v2, v3, vcc
	v_rsq_f32_e32 v14, v2
	v_lshl_add_u64 v[2:3], v[58:59], 0, s[8:9]
	global_store_short v[2:3], v1, off
	s_or_b64 s[8:9], s[36:37], s[14:15]
	v_add_f32_dpp v2, v88, v88 quad_perm:[1,0,3,2] row_mask:0xf bank_mask:0xf bound_ctrl:1
	v_mul_f32_e32 v1, 0x45800000, v14
	v_cndmask_b32_e32 v1, v14, v1, vcc
	v_add_f32_dpp v2, v2, v2 quad_perm:[2,3,0,1] row_mask:0xf bank_mask:0xf bound_ctrl:1
	v_mul_f32_e32 v1, v92, v1
	v_fma_f32 v1, v153, v1, v152
	v_add_f32_dpp v2, v2, v2 row_half_mirror row_mask:0xf bank_mask:0xf bound_ctrl:1
	s_waitcnt lgkmcnt(0)
	v_fmac_f32_e32 v1, v12, v93
	v_mul_f32_e32 v1, v6, v1
	v_add_f32_dpp v2, v2, v2 row_mirror row_mask:0xf bank_mask:0xf bound_ctrl:1
	s_lshl_b64 s[8:9], s[8:9], 10
	v_cvt_pk_bf16_f32 v1, v1, v0
	s_nop 1
	v_add_f32_dpp v2, v2, v2 row_bcast:15 row_mask:0xa bank_mask:0xf
	s_nop 1
	v_add_f32_dpp v2, v2, v2 row_bcast:31 row_mask:0xc bank_mask:0xf
	s_nop 0
	v_readlane_b32 s2, v2, 63
	v_mov_b32_e32 v2, s2
	v_fmac_f32_e32 v88, 0xbc800000, v2
	v_mul_f32_e32 v2, v88, v88
	v_mov_b32_e32 v3, v0
	s_nop 1
	v_mov_b32_dpp v3, v2 quad_perm:[1,0,3,2] row_mask:0xf bank_mask:0xf
	v_fmac_f32_e32 v3, v88, v88
	s_nop 1
	v_add_f32_dpp v2, v3, v3 quad_perm:[2,3,0,1] row_mask:0xf bank_mask:0xf bound_ctrl:1
	s_nop 1
	v_add_f32_dpp v2, v2, v2 row_half_mirror row_mask:0xf bank_mask:0xf bound_ctrl:1
	s_nop 1
	v_add_f32_dpp v2, v2, v2 row_mirror row_mask:0xf bank_mask:0xf bound_ctrl:1
	s_nop 0
	s_nop 1
	v_add_f32_dpp v2, v2, v2 row_bcast:15 row_mask:0xa bank_mask:0xf
	s_nop 1
	v_add_f32_dpp v2, v2, v2 row_bcast:31 row_mask:0xc bank_mask:0xf
	s_nop 0
	v_readlane_b32 s2, v2, 63
	v_mov_b32_e32 v2, s2
	v_fmamk_f32 v2, v2, 0x3c800000, v233
	v_mul_f32_e32 v3, 0x4b800000, v2
	v_cmp_gt_f32_e32 vcc, s82, v2
	s_nop 1
	v_cndmask_b32_e32 v2, v2, v3, vcc
	v_rsq_f32_e32 v12, v2
	v_lshl_add_u64 v[2:3], v[58:59], 0, s[8:9]
	global_store_short v[2:3], v1, off
	s_or_b64 s[8:9], s[36:37], s[16:17]
	v_mul_f32_e32 v1, 0x45800000, v12
	v_cndmask_b32_e32 v1, v12, v1, vcc
	v_mul_f32_e32 v1, v88, v1
	v_fma_f32 v1, v153, v1, v152
	v_fmac_f32_e32 v1, v13, v94
	s_lshl_b64 s[8:9], s[8:9], 10
	v_mul_f32_e32 v1, v7, v1
	v_lshl_add_u64 v[2:3], v[58:59], 0, s[8:9]
	s_mov_b32 s8, s3
	v_cvt_pk_bf16_f32 v1, v1, v0
	global_store_short v[2:3], v1, off
